# gate phase rewritten: one (token, head) per lane with all 128 channels in registers, no cross-lane reductions, 32 KiB of loads in flight per wave
# baseline (speedup 1.0000x reference)
; #define TIDX opaque_tid()
; #define BIDX opaque_bid()
; DEVI float bflo(unsigned u) { return __uint_as_float(u << 16); }
; DEVI float bfhi(unsigned u) { return __uint_as_float(u & 0xffff0000u); }
; DEVI void gate_phase(const Params& p, int j) {
;     ...
;   const float* nw = p.in[13] + j * 128;
;   const int tid = TIDX;
;   const int lane = tid & 63;
;   const int gw = BIDX * 4 + (tid >> 6), nwv = gridDim.x * 4;
;   const int half = lane >> 5, l31 = lane & 31;
;   const f32x4 w = *(const f32x4*)(nw + l31 * 4);
;   for (int t = gw; t < L; t += nwv) {
;     u32x2 ov[4], zv[4];
; #pragma unroll
;     for (int q = 0; q < 4; ++q) {
;       const int h = q * 2 + half;
;       ov[q] = *(const u32x2*)(r1 + (size_t)t * 3072 + 2048 + h * 128 + l31 * 4);
;       zv[q] = *(const u32x2*)(z + (size_t)t * 1024 + h * 128 + l31 * 4);
;     }
;     float ss[4];
; #pragma unroll
;     for (int q = 0; q < 4; ++q) {
;       const float o0 = bflo(ov[q].x), o1 = bfhi(ov[q].x), o2 = bflo(ov[q].y), o3 = bfhi(ov[q].y);
;       ss[q] = o0 * o0 + o1 * o1 + o2 * o2 + o3 * o3;
.LBB0_344:
	s_and_b64 vcc, exec, s[6:7]
	s_cbranch_vccz .LBB0_1572
	v_readlane_b32 s5, v247, 22
	s_cmp_gt_i32 s5, 1
	s_mov_b64 s[6:7], -1
	s_cbranch_scc0 .LBB0_1298
	v_readlane_b32 s0, v247, 22
	s_cmp_lt_i32 s0, 3
	s_mov_b64 s[0:1], -1
	s_cbranch_scc1 .LBB0_1239
	v_readlane_b32 s0, v247, 22
	s_cmp_gt_i32 s0, 3
	s_mov_b64 s[0:1], -1
	s_cbranch_scc0 .LBB0_352
	v_mov_b32_e32 v10, v206
	s_mov_b32 s0, s88
	s_lshl_b32 s0, s0, 2
	v_ashrrev_i32_e32 v8, 6, v10
	v_add_u32_e32 v0, s0, v8
	s_movk_i32 s1, 0x4010
	v_cmp_gt_i32_e32 vcc, s1, v0
	s_and_saveexec_b64 s[6:7], vcc
	v_readlane_b32 s16, v248, 10
	v_readlane_b32 s24, v248, 14
	v_readlane_b32 s17, v248, 11
	v_readlane_b32 s25, v248, 15
	s_mov_b32 s9, 0x9c53000
	s_mov_b32 s2, 0x800000
	s_movk_i32 s13, 0x400f
	s_brev_b32 s18, 60
	s_mov_b32 s34, 0x358637bd
	s_cbranch_execz .LBB0_351
	v_readlane_b32 s5, v247, 24
	v_readlane_b32 vcc_lo, v248, 40
	v_readlane_b32 vcc_hi, v248, 41
	s_lshl_b32 s5, s5, 9
	s_add_u32 vcc_lo, vcc_lo, s5
	s_addc_u32 vcc_hi, vcc_hi, 0
	s_add_u32 s10, s84, 0x9c53000
	s_addc_u32 s11, s85, 0
	s_add_u32 s0, s84, 0x6d5b240
	s_addc_u32 s1, s85, 0
	v_lshrrev_b32_e32 v192, 6, v206
	v_and_b32_e32 v167, 63, v206
	v_lshl_add_u32 v192, s88, 2, v192
	v_lshrrev_b32_e32 v190, 3, v167
	v_and_b32_e32 v191, 7, v167
	v_readfirstlane_b32 s5, v192
	v_lshlrev_b32_e32 v191, 8, v191
.Lgt_item:
	s_cmp_lt_u32 s5, 2050
	s_cbranch_scc0 .Lgt_done
	v_lshl_add_u32 v165, v192, 3, v190
	v_mul_u32_u24_e32 v162, 0x1800, v165
	v_add_u32_e32 v162, v162, v191
	v_add_u32_e32 v163, 0x1000, v162
	v_lshl_add_u32 v164, v165, 11, v191
	global_load_dwordx4 v[2:5], v163, s[10:11] offset:0
	global_load_dwordx4 v[6:9], v163, s[10:11] offset:16
	global_load_dwordx4 v[10:13], v163, s[10:11] offset:32
	global_load_dwordx4 v[14:17], v163, s[10:11] offset:48
	global_load_dwordx4 v[18:21], v163, s[10:11] offset:64
	global_load_dwordx4 v[22:25], v163, s[10:11] offset:80
	global_load_dwordx4 v[26:29], v163, s[10:11] offset:96
	global_load_dwordx4 v[30:33], v163, s[10:11] offset:112
	global_load_dwordx4 v[34:37], v163, s[10:11] offset:128
	global_load_dwordx4 v[38:41], v163, s[10:11] offset:144
	global_load_dwordx4 v[42:45], v163, s[10:11] offset:160
	global_load_dwordx4 v[46:49], v163, s[10:11] offset:176
	global_load_dwordx4 v[50:53], v163, s[10:11] offset:192
	global_load_dwordx4 v[54:57], v163, s[10:11] offset:208
	global_load_dwordx4 v[58:61], v163, s[10:11] offset:224
	global_load_dwordx4 v[62:65], v163, s[10:11] offset:240
	global_load_dwordx4 v[66:69], v164, s[0:1] offset:0
	global_load_dwordx4 v[70:73], v164, s[0:1] offset:16
	global_load_dwordx4 v[74:77], v164, s[0:1] offset:32
	global_load_dwordx4 v[78:81], v164, s[0:1] offset:48
	global_load_dwordx4 v[82:85], v164, s[0:1] offset:64
	global_load_dwordx4 v[86:89], v164, s[0:1] offset:80
	global_load_dwordx4 v[90:93], v164, s[0:1] offset:96
	global_load_dwordx4 v[94:97], v164, s[0:1] offset:112
	global_load_dwordx4 v[98:101], v164, s[0:1] offset:128
	global_load_dwordx4 v[102:105], v164, s[0:1] offset:144
	global_load_dwordx4 v[106:109], v164, s[0:1] offset:160
	global_load_dwordx4 v[110:113], v164, s[0:1] offset:176
	global_load_dwordx4 v[114:117], v164, s[0:1] offset:192
	global_load_dwordx4 v[118:121], v164, s[0:1] offset:208
	global_load_dwordx4 v[122:125], v164, s[0:1] offset:224
	global_load_dwordx4 v[126:129], v164, s[0:1] offset:240
	v_mov_b32_e32 v182, 0
	v_mov_b32_e32 v183, 0
	v_mov_b32_e32 v184, 0
	v_mov_b32_e32 v185, 0
	s_waitcnt vmcnt(31)
	v_lshlrev_b32_e32 v166, 16, v2
	v_and_b32_e32 v167, 0xffff0000, v2
	v_fma_f32 v182, v166, v166, v182
	v_fma_f32 v183, v167, v167, v183
	v_lshlrev_b32_e32 v166, 16, v3
	v_and_b32_e32 v167, 0xffff0000, v3
	v_fma_f32 v184, v166, v166, v184
	v_fma_f32 v185, v167, v167, v185
	v_lshlrev_b32_e32 v166, 16, v4
	v_and_b32_e32 v167, 0xffff0000, v4
	v_fma_f32 v182, v166, v166, v182
	v_fma_f32 v183, v167, v167, v183
	v_lshlrev_b32_e32 v166, 16, v5
	v_and_b32_e32 v167, 0xffff0000, v5
	v_fma_f32 v184, v166, v166, v184
	v_fma_f32 v185, v167, v167, v185
	s_waitcnt vmcnt(30)
	v_lshlrev_b32_e32 v166, 16, v6
	v_and_b32_e32 v167, 0xffff0000, v6
	v_fma_f32 v182, v166, v166, v182
	v_fma_f32 v183, v167, v167, v183
	v_lshlrev_b32_e32 v166, 16, v7
	v_and_b32_e32 v167, 0xffff0000, v7
	v_fma_f32 v184, v166, v166, v184
	v_fma_f32 v185, v167, v167, v185
	v_lshlrev_b32_e32 v166, 16, v8
	v_and_b32_e32 v167, 0xffff0000, v8
	v_fma_f32 v182, v166, v166, v182
	v_fma_f32 v183, v167, v167, v183
	v_lshlrev_b32_e32 v166, 16, v9
	v_and_b32_e32 v167, 0xffff0000, v9
	v_fma_f32 v184, v166, v166, v184
	v_fma_f32 v185, v167, v167, v185
	s_waitcnt vmcnt(29)
	v_lshlrev_b32_e32 v166, 16, v10
	v_and_b32_e32 v167, 0xffff0000, v10
	v_fma_f32 v182, v166, v166, v182
	v_fma_f32 v183, v167, v167, v183
	v_lshlrev_b32_e32 v166, 16, v11
	v_and_b32_e32 v167, 0xffff0000, v11
	v_fma_f32 v184, v166, v166, v184
	v_fma_f32 v185, v167, v167, v185
	v_lshlrev_b32_e32 v166, 16, v12
	v_and_b32_e32 v167, 0xffff0000, v12
	v_fma_f32 v182, v166, v166, v182
	v_fma_f32 v183, v167, v167, v183
	v_lshlrev_b32_e32 v166, 16, v13
	v_and_b32_e32 v167, 0xffff0000, v13
	v_fma_f32 v184, v166, v166, v184
	v_fma_f32 v185, v167, v167, v185
	s_waitcnt vmcnt(28)
	v_lshlrev_b32_e32 v166, 16, v14
	v_and_b32_e32 v167, 0xffff0000, v14
	v_fma_f32 v182, v166, v166, v182
	v_fma_f32 v183, v167, v167, v183
	v_lshlrev_b32_e32 v166, 16, v15
	v_and_b32_e32 v167, 0xffff0000, v15
	v_fma_f32 v184, v166, v166, v184
	v_fma_f32 v185, v167, v167, v185
	v_lshlrev_b32_e32 v166, 16, v16
	v_and_b32_e32 v167, 0xffff0000, v16
	v_fma_f32 v182, v166, v166, v182
	v_fma_f32 v183, v167, v167, v183
	v_lshlrev_b32_e32 v166, 16, v17
	v_and_b32_e32 v167, 0xffff0000, v17
	v_fma_f32 v184, v166, v166, v184
	v_fma_f32 v185, v167, v167, v185
	s_waitcnt vmcnt(27)
; DEVI float bflo(unsigned u) { return __uint_as_float(u << 16); }
; DEVI float bfhi(unsigned u) { return __uint_as_float(u & 0xffff0000u); }
; DEVI void gate_phase(const Params& p, int j) {
;     ...
;     float ss[4];
; #pragma unroll
;     for (int q = 0; q < 4; ++q) {
;       const float o0 = bflo(ov[q].x), o1 = bfhi(ov[q].x), o2 = bflo(ov[q].y), o3 = bfhi(ov[q].y);
;       ss[q] = o0 * o0 + o1 * o1 + o2 * o2 + o3 * o3;
	v_lshlrev_b32_e32 v166, 16, v18
	v_and_b32_e32 v167, 0xffff0000, v18
	v_fma_f32 v182, v166, v166, v182
	v_fma_f32 v183, v167, v167, v183
	v_lshlrev_b32_e32 v166, 16, v19
	v_and_b32_e32 v167, 0xffff0000, v19
	v_fma_f32 v184, v166, v166, v184
	v_fma_f32 v185, v167, v167, v185
	v_lshlrev_b32_e32 v166, 16, v20
	v_and_b32_e32 v167, 0xffff0000, v20
	v_fma_f32 v182, v166, v166, v182
	v_fma_f32 v183, v167, v167, v183
	v_lshlrev_b32_e32 v166, 16, v21
	v_and_b32_e32 v167, 0xffff0000, v21
	v_fma_f32 v184, v166, v166, v184
	v_fma_f32 v185, v167, v167, v185
	s_waitcnt vmcnt(26)
	v_lshlrev_b32_e32 v166, 16, v22
	v_and_b32_e32 v167, 0xffff0000, v22
	v_fma_f32 v182, v166, v166, v182
	v_fma_f32 v183, v167, v167, v183
	v_lshlrev_b32_e32 v166, 16, v23
	v_and_b32_e32 v167, 0xffff0000, v23
	v_fma_f32 v184, v166, v166, v184
	v_fma_f32 v185, v167, v167, v185
	v_lshlrev_b32_e32 v166, 16, v24
	v_and_b32_e32 v167, 0xffff0000, v24
	v_fma_f32 v182, v166, v166, v182
	v_fma_f32 v183, v167, v167, v183
	v_lshlrev_b32_e32 v166, 16, v25
	v_and_b32_e32 v167, 0xffff0000, v25
	v_fma_f32 v184, v166, v166, v184
	v_fma_f32 v185, v167, v167, v185
	s_waitcnt vmcnt(25)
	v_lshlrev_b32_e32 v166, 16, v26
	v_and_b32_e32 v167, 0xffff0000, v26
	v_fma_f32 v182, v166, v166, v182
	v_fma_f32 v183, v167, v167, v183
	v_lshlrev_b32_e32 v166, 16, v27
	v_and_b32_e32 v167, 0xffff0000, v27
	v_fma_f32 v184, v166, v166, v184
	v_fma_f32 v185, v167, v167, v185
	v_lshlrev_b32_e32 v166, 16, v28
	v_and_b32_e32 v167, 0xffff0000, v28
	v_fma_f32 v182, v166, v166, v182
	v_fma_f32 v183, v167, v167, v183
	v_lshlrev_b32_e32 v166, 16, v29
	v_and_b32_e32 v167, 0xffff0000, v29
	v_fma_f32 v184, v166, v166, v184
	v_fma_f32 v185, v167, v167, v185
	s_waitcnt vmcnt(24)
	v_lshlrev_b32_e32 v166, 16, v30
	v_and_b32_e32 v167, 0xffff0000, v30
	v_fma_f32 v182, v166, v166, v182
	v_fma_f32 v183, v167, v167, v183
	v_lshlrev_b32_e32 v166, 16, v31
	v_and_b32_e32 v167, 0xffff0000, v31
	v_fma_f32 v184, v166, v166, v184
	v_fma_f32 v185, v167, v167, v185
	v_lshlrev_b32_e32 v166, 16, v32
	v_and_b32_e32 v167, 0xffff0000, v32
	v_fma_f32 v182, v166, v166, v182
	v_fma_f32 v183, v167, v167, v183
	v_lshlrev_b32_e32 v166, 16, v33
	v_and_b32_e32 v167, 0xffff0000, v33
	v_fma_f32 v184, v166, v166, v184
	v_fma_f32 v185, v167, v167, v185
	s_waitcnt vmcnt(23)
	v_lshlrev_b32_e32 v166, 16, v34
	v_and_b32_e32 v167, 0xffff0000, v34
	v_fma_f32 v182, v166, v166, v182
	v_fma_f32 v183, v167, v167, v183
	v_lshlrev_b32_e32 v166, 16, v35
	v_and_b32_e32 v167, 0xffff0000, v35
	v_fma_f32 v184, v166, v166, v184
	v_fma_f32 v185, v167, v167, v185
	v_lshlrev_b32_e32 v166, 16, v36
	v_and_b32_e32 v167, 0xffff0000, v36
	v_fma_f32 v182, v166, v166, v182
	v_fma_f32 v183, v167, v167, v183
	v_lshlrev_b32_e32 v166, 16, v37
	v_and_b32_e32 v167, 0xffff0000, v37
	v_fma_f32 v184, v166, v166, v184
	v_fma_f32 v185, v167, v167, v185
	s_waitcnt vmcnt(22)
	v_lshlrev_b32_e32 v166, 16, v38
	v_and_b32_e32 v167, 0xffff0000, v38
	v_fma_f32 v182, v166, v166, v182
	v_fma_f32 v183, v167, v167, v183
	v_lshlrev_b32_e32 v166, 16, v39
	v_and_b32_e32 v167, 0xffff0000, v39
	v_fma_f32 v184, v166, v166, v184
	v_fma_f32 v185, v167, v167, v185
	v_lshlrev_b32_e32 v166, 16, v40
	v_and_b32_e32 v167, 0xffff0000, v40
	v_fma_f32 v182, v166, v166, v182
	v_fma_f32 v183, v167, v167, v183
	v_lshlrev_b32_e32 v166, 16, v41
	v_and_b32_e32 v167, 0xffff0000, v41
	v_fma_f32 v184, v166, v166, v184
	v_fma_f32 v185, v167, v167, v185
	s_waitcnt vmcnt(21)
	v_lshlrev_b32_e32 v166, 16, v42
	v_and_b32_e32 v167, 0xffff0000, v42
	v_fma_f32 v182, v166, v166, v182
	v_fma_f32 v183, v167, v167, v183
	v_lshlrev_b32_e32 v166, 16, v43
	v_and_b32_e32 v167, 0xffff0000, v43
	v_fma_f32 v184, v166, v166, v184
	v_fma_f32 v185, v167, v167, v185
	v_lshlrev_b32_e32 v166, 16, v44
	v_and_b32_e32 v167, 0xffff0000, v44
	v_fma_f32 v182, v166, v166, v182
	v_fma_f32 v183, v167, v167, v183
	v_lshlrev_b32_e32 v166, 16, v45
	v_and_b32_e32 v167, 0xffff0000, v45
	v_fma_f32 v184, v166, v166, v184
	v_fma_f32 v185, v167, v167, v185
	s_waitcnt vmcnt(20)
	v_lshlrev_b32_e32 v166, 16, v46
	v_and_b32_e32 v167, 0xffff0000, v46
	v_fma_f32 v182, v166, v166, v182
	v_fma_f32 v183, v167, v167, v183
	v_lshlrev_b32_e32 v166, 16, v47
	v_and_b32_e32 v167, 0xffff0000, v47
	v_fma_f32 v184, v166, v166, v184
	v_fma_f32 v185, v167, v167, v185
	v_lshlrev_b32_e32 v166, 16, v48
	v_and_b32_e32 v167, 0xffff0000, v48
	v_fma_f32 v182, v166, v166, v182
	v_fma_f32 v183, v167, v167, v183
	v_lshlrev_b32_e32 v166, 16, v49
	v_and_b32_e32 v167, 0xffff0000, v49
	v_fma_f32 v184, v166, v166, v184
	v_fma_f32 v185, v167, v167, v185
	s_waitcnt vmcnt(19)
	v_lshlrev_b32_e32 v166, 16, v50
	v_and_b32_e32 v167, 0xffff0000, v50
	v_fma_f32 v182, v166, v166, v182
	v_fma_f32 v183, v167, v167, v183
	v_lshlrev_b32_e32 v166, 16, v51
	v_and_b32_e32 v167, 0xffff0000, v51
	v_fma_f32 v184, v166, v166, v184
	v_fma_f32 v185, v167, v167, v185
	v_lshlrev_b32_e32 v166, 16, v52
	v_and_b32_e32 v167, 0xffff0000, v52
	v_fma_f32 v182, v166, v166, v182
	v_fma_f32 v183, v167, v167, v183
	v_lshlrev_b32_e32 v166, 16, v53
	v_and_b32_e32 v167, 0xffff0000, v53
	v_fma_f32 v184, v166, v166, v184
	v_fma_f32 v185, v167, v167, v185
	s_waitcnt vmcnt(18)
	v_lshlrev_b32_e32 v166, 16, v54
	v_and_b32_e32 v167, 0xffff0000, v54
	v_fma_f32 v182, v166, v166, v182
	v_fma_f32 v183, v167, v167, v183
	v_lshlrev_b32_e32 v166, 16, v55
	v_and_b32_e32 v167, 0xffff0000, v55
	v_fma_f32 v184, v166, v166, v184
	v_fma_f32 v185, v167, v167, v185
	v_lshlrev_b32_e32 v166, 16, v56
	v_and_b32_e32 v167, 0xffff0000, v56
	v_fma_f32 v182, v166, v166, v182
	v_fma_f32 v183, v167, v167, v183
	v_lshlrev_b32_e32 v166, 16, v57
	v_and_b32_e32 v167, 0xffff0000, v57
	v_fma_f32 v184, v166, v166, v184
	v_fma_f32 v185, v167, v167, v185
	s_waitcnt vmcnt(17)
; DEVI float bflo(unsigned u) { return __uint_as_float(u << 16); }
; DEVI float bfhi(unsigned u) { return __uint_as_float(u & 0xffff0000u); }
; DEVI void gate_phase(const Params& p, int j) {
;     ...
; #pragma unroll
;     for (int q = 0; q < 4; ++q) {
;       const int h = q * 2 + half;
;       const float r = rsqrtf(ss[q] * (1.f / 128.f) + 1e-6f);
;       const float o[4] = {bflo(ov[q].x), bfhi(ov[q].x), bflo(ov[q].y), bfhi(ov[q].y)};
;       const float zz[4] = {bflo(zv[q].x), bfhi(zv[q].x), bflo(zv[q].y), bfhi(zv[q].y)};
;       float y[4];
; #pragma unroll
;       for (int e = 0; e < 4; ++e) y[e] = o[e] * r * w[e] * (zz[e] / (1.f + __expf(-zz[e])));
;       *(u32x2*)(r1 + (size_t)t * 3072 + h * 128 + l31 * 4) = u32x2{pack2(y[0], y[1]), pack2(y[2], y[3])};
	v_lshlrev_b32_e32 v166, 16, v58
	v_and_b32_e32 v167, 0xffff0000, v58
	v_fma_f32 v182, v166, v166, v182
	v_fma_f32 v183, v167, v167, v183
	v_lshlrev_b32_e32 v166, 16, v59
	v_and_b32_e32 v167, 0xffff0000, v59
	v_fma_f32 v184, v166, v166, v184
	v_fma_f32 v185, v167, v167, v185
	v_lshlrev_b32_e32 v166, 16, v60
	v_and_b32_e32 v167, 0xffff0000, v60
	v_fma_f32 v182, v166, v166, v182
	v_fma_f32 v183, v167, v167, v183
	v_lshlrev_b32_e32 v166, 16, v61
	v_and_b32_e32 v167, 0xffff0000, v61
	v_fma_f32 v184, v166, v166, v184
	v_fma_f32 v185, v167, v167, v185
	s_waitcnt vmcnt(16)
	v_lshlrev_b32_e32 v166, 16, v62
	v_and_b32_e32 v167, 0xffff0000, v62
	v_fma_f32 v182, v166, v166, v182
	v_fma_f32 v183, v167, v167, v183
	v_lshlrev_b32_e32 v166, 16, v63
	v_and_b32_e32 v167, 0xffff0000, v63
	v_fma_f32 v184, v166, v166, v184
	v_fma_f32 v185, v167, v167, v185
	v_lshlrev_b32_e32 v166, 16, v64
	v_and_b32_e32 v167, 0xffff0000, v64
	v_fma_f32 v182, v166, v166, v182
	v_fma_f32 v183, v167, v167, v183
	v_lshlrev_b32_e32 v166, 16, v65
	v_and_b32_e32 v167, 0xffff0000, v65
	v_fma_f32 v184, v166, v166, v184
	v_fma_f32 v185, v167, v167, v185
	v_add_f32_e32 v182, v182, v183
	v_add_f32_e32 v184, v184, v185
	v_add_f32_e32 v182, v182, v184
	v_mov_b32_e32 v183, 0x358637bd
	v_fmac_f32_e32 v183, 0x3c000000, v182
	v_rsq_f32_e32 v182, v183
	s_nop 0
	global_load_dwordx4 v[130:133], v1, vcc offset:0
	global_load_dwordx4 v[134:137], v1, vcc offset:16
	global_load_dwordx4 v[138:141], v1, vcc offset:32
	global_load_dwordx4 v[142:145], v1, vcc offset:48
	global_load_dwordx4 v[146:149], v1, vcc offset:64
	global_load_dwordx4 v[150:153], v1, vcc offset:80
	global_load_dwordx4 v[154:157], v1, vcc offset:96
	global_load_dwordx4 v[158:161], v1, vcc offset:112
	s_waitcnt vmcnt(0)
	v_lshlrev_b32_e32 v166, 16, v66
	v_and_b32_e32 v167, 0xffff0000, v66
	v_mul_f32_e32 v168, 0xbfb8aa3b, v166
	v_mul_f32_e32 v169, 0xbfb8aa3b, v167
	v_exp_f32_e32 v168, v168
	v_exp_f32_e32 v169, v169
	v_lshlrev_b32_e32 v170, 16, v2
	v_and_b32_e32 v171, 0xffff0000, v2
	v_add_f32_e32 v168, 1.0, v168
	v_add_f32_e32 v169, 1.0, v169
	v_rcp_f32_e32 v168, v168
	v_rcp_f32_e32 v169, v169
	v_mul_f32_e32 v170, v170, v182
	v_mul_f32_e32 v171, v171, v182
	v_mul_f32_e32 v166, v166, v168
	v_mul_f32_e32 v167, v167, v169
	v_mul_f32_e32 v170, v170, v130
	v_mul_f32_e32 v171, v171, v131
	v_mul_f32_e32 v170, v170, v166
	v_mul_f32_e32 v171, v171, v167
	v_cvt_pk_bf16_f32 v2, v170, v171
	v_lshlrev_b32_e32 v166, 16, v67
	v_and_b32_e32 v167, 0xffff0000, v67
	v_mul_f32_e32 v168, 0xbfb8aa3b, v166
	v_mul_f32_e32 v169, 0xbfb8aa3b, v167
	v_exp_f32_e32 v168, v168
	v_exp_f32_e32 v169, v169
	v_lshlrev_b32_e32 v170, 16, v3
	v_and_b32_e32 v171, 0xffff0000, v3
	v_add_f32_e32 v168, 1.0, v168
	v_add_f32_e32 v169, 1.0, v169
	v_rcp_f32_e32 v168, v168
	v_rcp_f32_e32 v169, v169
	v_mul_f32_e32 v170, v170, v182
	v_mul_f32_e32 v171, v171, v182
	v_mul_f32_e32 v166, v166, v168
	v_mul_f32_e32 v167, v167, v169
	v_mul_f32_e32 v170, v170, v132
	v_mul_f32_e32 v171, v171, v133
	v_mul_f32_e32 v170, v170, v166
	v_mul_f32_e32 v171, v171, v167
	v_cvt_pk_bf16_f32 v3, v170, v171
	v_lshlrev_b32_e32 v166, 16, v68
	v_and_b32_e32 v167, 0xffff0000, v68
	v_mul_f32_e32 v168, 0xbfb8aa3b, v166
	v_mul_f32_e32 v169, 0xbfb8aa3b, v167
	v_exp_f32_e32 v168, v168
	v_exp_f32_e32 v169, v169
	v_lshlrev_b32_e32 v170, 16, v4
	v_and_b32_e32 v171, 0xffff0000, v4
	v_add_f32_e32 v168, 1.0, v168
	v_add_f32_e32 v169, 1.0, v169
	v_rcp_f32_e32 v168, v168
	v_rcp_f32_e32 v169, v169
	v_mul_f32_e32 v170, v170, v182
	v_mul_f32_e32 v171, v171, v182
	v_mul_f32_e32 v166, v166, v168
	v_mul_f32_e32 v167, v167, v169
	v_mul_f32_e32 v170, v170, v134
	v_mul_f32_e32 v171, v171, v135
	v_mul_f32_e32 v170, v170, v166
	v_mul_f32_e32 v171, v171, v167
	v_cvt_pk_bf16_f32 v4, v170, v171
	v_lshlrev_b32_e32 v166, 16, v69
	v_and_b32_e32 v167, 0xffff0000, v69
	v_mul_f32_e32 v168, 0xbfb8aa3b, v166
	v_mul_f32_e32 v169, 0xbfb8aa3b, v167
	v_exp_f32_e32 v168, v168
	v_exp_f32_e32 v169, v169
	v_lshlrev_b32_e32 v170, 16, v5
	v_and_b32_e32 v171, 0xffff0000, v5
	v_add_f32_e32 v168, 1.0, v168
	v_add_f32_e32 v169, 1.0, v169
	v_rcp_f32_e32 v168, v168
	v_rcp_f32_e32 v169, v169
	v_mul_f32_e32 v170, v170, v182
	v_mul_f32_e32 v171, v171, v182
	v_mul_f32_e32 v166, v166, v168
	v_mul_f32_e32 v167, v167, v169
	v_mul_f32_e32 v170, v170, v136
	v_mul_f32_e32 v171, v171, v137
	v_mul_f32_e32 v170, v170, v166
	v_mul_f32_e32 v171, v171, v167
	v_cvt_pk_bf16_f32 v5, v170, v171
	v_lshlrev_b32_e32 v166, 16, v70
	v_and_b32_e32 v167, 0xffff0000, v70
	v_mul_f32_e32 v168, 0xbfb8aa3b, v166
	v_mul_f32_e32 v169, 0xbfb8aa3b, v167
	v_exp_f32_e32 v168, v168
	v_exp_f32_e32 v169, v169
	v_lshlrev_b32_e32 v170, 16, v6
	v_and_b32_e32 v171, 0xffff0000, v6
	v_add_f32_e32 v168, 1.0, v168
	v_add_f32_e32 v169, 1.0, v169
	v_rcp_f32_e32 v168, v168
	v_rcp_f32_e32 v169, v169
	v_mul_f32_e32 v170, v170, v182
	v_mul_f32_e32 v171, v171, v182
	v_mul_f32_e32 v166, v166, v168
	v_mul_f32_e32 v167, v167, v169
	v_mul_f32_e32 v170, v170, v138
	v_mul_f32_e32 v171, v171, v139
	v_mul_f32_e32 v170, v170, v166
	v_mul_f32_e32 v171, v171, v167
	v_cvt_pk_bf16_f32 v6, v170, v171
	v_lshlrev_b32_e32 v166, 16, v71
	v_and_b32_e32 v167, 0xffff0000, v71
	v_mul_f32_e32 v168, 0xbfb8aa3b, v166
	v_mul_f32_e32 v169, 0xbfb8aa3b, v167
	v_exp_f32_e32 v168, v168
	v_exp_f32_e32 v169, v169
	v_lshlrev_b32_e32 v170, 16, v7
	v_and_b32_e32 v171, 0xffff0000, v7
	v_add_f32_e32 v168, 1.0, v168
	v_add_f32_e32 v169, 1.0, v169
	v_rcp_f32_e32 v168, v168
	v_rcp_f32_e32 v169, v169
	v_mul_f32_e32 v170, v170, v182
	v_mul_f32_e32 v171, v171, v182
	v_mul_f32_e32 v166, v166, v168
	v_mul_f32_e32 v167, v167, v169
	v_mul_f32_e32 v170, v170, v140
; DEVI float bflo(unsigned u) { return __uint_as_float(u << 16); }
; DEVI float bfhi(unsigned u) { return __uint_as_float(u & 0xffff0000u); }
; DEVI void gate_phase(const Params& p, int j) {
;     ...
; #pragma unroll
;     for (int q = 0; q < 4; ++q) {
;       const int h = q * 2 + half;
;       const float r = rsqrtf(ss[q] * (1.f / 128.f) + 1e-6f);
;       const float o[4] = {bflo(ov[q].x), bfhi(ov[q].x), bflo(ov[q].y), bfhi(ov[q].y)};
;       const float zz[4] = {bflo(zv[q].x), bfhi(zv[q].x), bflo(zv[q].y), bfhi(zv[q].y)};
;       float y[4];
; #pragma unroll
;       for (int e = 0; e < 4; ++e) y[e] = o[e] * r * w[e] * (zz[e] / (1.f + __expf(-zz[e])));
;       *(u32x2*)(r1 + (size_t)t * 3072 + h * 128 + l31 * 4) = u32x2{pack2(y[0], y[1]), pack2(y[2], y[3])};
	v_mul_f32_e32 v171, v171, v141
	v_mul_f32_e32 v170, v170, v166
	v_mul_f32_e32 v171, v171, v167
	v_cvt_pk_bf16_f32 v7, v170, v171
	v_lshlrev_b32_e32 v166, 16, v72
	v_and_b32_e32 v167, 0xffff0000, v72
	v_mul_f32_e32 v168, 0xbfb8aa3b, v166
	v_mul_f32_e32 v169, 0xbfb8aa3b, v167
	v_exp_f32_e32 v168, v168
	v_exp_f32_e32 v169, v169
	v_lshlrev_b32_e32 v170, 16, v8
	v_and_b32_e32 v171, 0xffff0000, v8
	v_add_f32_e32 v168, 1.0, v168
	v_add_f32_e32 v169, 1.0, v169
	v_rcp_f32_e32 v168, v168
	v_rcp_f32_e32 v169, v169
	v_mul_f32_e32 v170, v170, v182
	v_mul_f32_e32 v171, v171, v182
	v_mul_f32_e32 v166, v166, v168
	v_mul_f32_e32 v167, v167, v169
	v_mul_f32_e32 v170, v170, v142
	v_mul_f32_e32 v171, v171, v143
	v_mul_f32_e32 v170, v170, v166
	v_mul_f32_e32 v171, v171, v167
	v_cvt_pk_bf16_f32 v8, v170, v171
	v_lshlrev_b32_e32 v166, 16, v73
	v_and_b32_e32 v167, 0xffff0000, v73
	v_mul_f32_e32 v168, 0xbfb8aa3b, v166
	v_mul_f32_e32 v169, 0xbfb8aa3b, v167
	v_exp_f32_e32 v168, v168
	v_exp_f32_e32 v169, v169
	v_lshlrev_b32_e32 v170, 16, v9
	v_and_b32_e32 v171, 0xffff0000, v9
	v_add_f32_e32 v168, 1.0, v168
	v_add_f32_e32 v169, 1.0, v169
	v_rcp_f32_e32 v168, v168
	v_rcp_f32_e32 v169, v169
	v_mul_f32_e32 v170, v170, v182
	v_mul_f32_e32 v171, v171, v182
	v_mul_f32_e32 v166, v166, v168
	v_mul_f32_e32 v167, v167, v169
	v_mul_f32_e32 v170, v170, v144
	v_mul_f32_e32 v171, v171, v145
	v_mul_f32_e32 v170, v170, v166
	v_mul_f32_e32 v171, v171, v167
	v_cvt_pk_bf16_f32 v9, v170, v171
	v_lshlrev_b32_e32 v166, 16, v74
	v_and_b32_e32 v167, 0xffff0000, v74
	v_mul_f32_e32 v168, 0xbfb8aa3b, v166
	v_mul_f32_e32 v169, 0xbfb8aa3b, v167
	v_exp_f32_e32 v168, v168
	v_exp_f32_e32 v169, v169
	v_lshlrev_b32_e32 v170, 16, v10
	v_and_b32_e32 v171, 0xffff0000, v10
	v_add_f32_e32 v168, 1.0, v168
	v_add_f32_e32 v169, 1.0, v169
	v_rcp_f32_e32 v168, v168
	v_rcp_f32_e32 v169, v169
	v_mul_f32_e32 v170, v170, v182
	v_mul_f32_e32 v171, v171, v182
	v_mul_f32_e32 v166, v166, v168
	v_mul_f32_e32 v167, v167, v169
	v_mul_f32_e32 v170, v170, v146
	v_mul_f32_e32 v171, v171, v147
	v_mul_f32_e32 v170, v170, v166
	v_mul_f32_e32 v171, v171, v167
	v_cvt_pk_bf16_f32 v10, v170, v171
	v_lshlrev_b32_e32 v166, 16, v75
	v_and_b32_e32 v167, 0xffff0000, v75
	v_mul_f32_e32 v168, 0xbfb8aa3b, v166
	v_mul_f32_e32 v169, 0xbfb8aa3b, v167
	v_exp_f32_e32 v168, v168
	v_exp_f32_e32 v169, v169
	v_lshlrev_b32_e32 v170, 16, v11
	v_and_b32_e32 v171, 0xffff0000, v11
	v_add_f32_e32 v168, 1.0, v168
	v_add_f32_e32 v169, 1.0, v169
	v_rcp_f32_e32 v168, v168
	v_rcp_f32_e32 v169, v169
	v_mul_f32_e32 v170, v170, v182
	v_mul_f32_e32 v171, v171, v182
	v_mul_f32_e32 v166, v166, v168
	v_mul_f32_e32 v167, v167, v169
	v_mul_f32_e32 v170, v170, v148
	v_mul_f32_e32 v171, v171, v149
	v_mul_f32_e32 v170, v170, v166
	v_mul_f32_e32 v171, v171, v167
	v_cvt_pk_bf16_f32 v11, v170, v171
	v_lshlrev_b32_e32 v166, 16, v76
	v_and_b32_e32 v167, 0xffff0000, v76
	v_mul_f32_e32 v168, 0xbfb8aa3b, v166
	v_mul_f32_e32 v169, 0xbfb8aa3b, v167
	v_exp_f32_e32 v168, v168
	v_exp_f32_e32 v169, v169
	v_lshlrev_b32_e32 v170, 16, v12
	v_and_b32_e32 v171, 0xffff0000, v12
	v_add_f32_e32 v168, 1.0, v168
	v_add_f32_e32 v169, 1.0, v169
	v_rcp_f32_e32 v168, v168
	v_rcp_f32_e32 v169, v169
	v_mul_f32_e32 v170, v170, v182
	v_mul_f32_e32 v171, v171, v182
	v_mul_f32_e32 v166, v166, v168
	v_mul_f32_e32 v167, v167, v169
	v_mul_f32_e32 v170, v170, v150
	v_mul_f32_e32 v171, v171, v151
	v_mul_f32_e32 v170, v170, v166
	v_mul_f32_e32 v171, v171, v167
	v_cvt_pk_bf16_f32 v12, v170, v171
	v_lshlrev_b32_e32 v166, 16, v77
	v_and_b32_e32 v167, 0xffff0000, v77
	v_mul_f32_e32 v168, 0xbfb8aa3b, v166
	v_mul_f32_e32 v169, 0xbfb8aa3b, v167
	v_exp_f32_e32 v168, v168
	v_exp_f32_e32 v169, v169
	v_lshlrev_b32_e32 v170, 16, v13
	v_and_b32_e32 v171, 0xffff0000, v13
	v_add_f32_e32 v168, 1.0, v168
	v_add_f32_e32 v169, 1.0, v169
	v_rcp_f32_e32 v168, v168
	v_rcp_f32_e32 v169, v169
	v_mul_f32_e32 v170, v170, v182
	v_mul_f32_e32 v171, v171, v182
	v_mul_f32_e32 v166, v166, v168
	v_mul_f32_e32 v167, v167, v169
	v_mul_f32_e32 v170, v170, v152
	v_mul_f32_e32 v171, v171, v153
	v_mul_f32_e32 v170, v170, v166
	v_mul_f32_e32 v171, v171, v167
	v_cvt_pk_bf16_f32 v13, v170, v171
	v_lshlrev_b32_e32 v166, 16, v78
	v_and_b32_e32 v167, 0xffff0000, v78
	v_mul_f32_e32 v168, 0xbfb8aa3b, v166
	v_mul_f32_e32 v169, 0xbfb8aa3b, v167
	v_exp_f32_e32 v168, v168
	v_exp_f32_e32 v169, v169
	v_lshlrev_b32_e32 v170, 16, v14
	v_and_b32_e32 v171, 0xffff0000, v14
	v_add_f32_e32 v168, 1.0, v168
	v_add_f32_e32 v169, 1.0, v169
	v_rcp_f32_e32 v168, v168
	v_rcp_f32_e32 v169, v169
	v_mul_f32_e32 v170, v170, v182
	v_mul_f32_e32 v171, v171, v182
	v_mul_f32_e32 v166, v166, v168
	v_mul_f32_e32 v167, v167, v169
	v_mul_f32_e32 v170, v170, v154
	v_mul_f32_e32 v171, v171, v155
	v_mul_f32_e32 v170, v170, v166
	v_mul_f32_e32 v171, v171, v167
	v_cvt_pk_bf16_f32 v14, v170, v171
	v_lshlrev_b32_e32 v166, 16, v79
	v_and_b32_e32 v167, 0xffff0000, v79
	v_mul_f32_e32 v168, 0xbfb8aa3b, v166
	v_mul_f32_e32 v169, 0xbfb8aa3b, v167
	v_exp_f32_e32 v168, v168
	v_exp_f32_e32 v169, v169
	v_lshlrev_b32_e32 v170, 16, v15
	v_and_b32_e32 v171, 0xffff0000, v15
	v_add_f32_e32 v168, 1.0, v168
	v_add_f32_e32 v169, 1.0, v169
	v_rcp_f32_e32 v168, v168
	v_rcp_f32_e32 v169, v169
	v_mul_f32_e32 v170, v170, v182
	v_mul_f32_e32 v171, v171, v182
	v_mul_f32_e32 v166, v166, v168
	v_mul_f32_e32 v167, v167, v169
	v_mul_f32_e32 v170, v170, v156
	v_mul_f32_e32 v171, v171, v157
	v_mul_f32_e32 v170, v170, v166
	v_mul_f32_e32 v171, v171, v167
	v_cvt_pk_bf16_f32 v15, v170, v171
	v_lshlrev_b32_e32 v166, 16, v80
	v_and_b32_e32 v167, 0xffff0000, v80
	v_mul_f32_e32 v168, 0xbfb8aa3b, v166
	v_mul_f32_e32 v169, 0xbfb8aa3b, v167
; DEVI float bflo(unsigned u) { return __uint_as_float(u << 16); }
; DEVI float bfhi(unsigned u) { return __uint_as_float(u & 0xffff0000u); }
; DEVI void gate_phase(const Params& p, int j) {
;     ...
;   const f32x4 w = *(const f32x4*)(nw + l31 * 4);
;     ...
; #pragma unroll
;     for (int q = 0; q < 4; ++q) {
;       const int h = q * 2 + half;
;       const float r = rsqrtf(ss[q] * (1.f / 128.f) + 1e-6f);
;       const float o[4] = {bflo(ov[q].x), bfhi(ov[q].x), bflo(ov[q].y), bfhi(ov[q].y)};
;       const float zz[4] = {bflo(zv[q].x), bfhi(zv[q].x), bflo(zv[q].y), bfhi(zv[q].y)};
;       float y[4];
; #pragma unroll
;       for (int e = 0; e < 4; ++e) y[e] = o[e] * r * w[e] * (zz[e] / (1.f + __expf(-zz[e])));
;       *(u32x2*)(r1 + (size_t)t * 3072 + h * 128 + l31 * 4) = u32x2{pack2(y[0], y[1]), pack2(y[2], y[3])};
	v_exp_f32_e32 v168, v168
	v_exp_f32_e32 v169, v169
	v_lshlrev_b32_e32 v170, 16, v16
	v_and_b32_e32 v171, 0xffff0000, v16
	v_add_f32_e32 v168, 1.0, v168
	v_add_f32_e32 v169, 1.0, v169
	v_rcp_f32_e32 v168, v168
	v_rcp_f32_e32 v169, v169
	v_mul_f32_e32 v170, v170, v182
	v_mul_f32_e32 v171, v171, v182
	v_mul_f32_e32 v166, v166, v168
	v_mul_f32_e32 v167, v167, v169
	v_mul_f32_e32 v170, v170, v158
	v_mul_f32_e32 v171, v171, v159
	v_mul_f32_e32 v170, v170, v166
	v_mul_f32_e32 v171, v171, v167
	v_cvt_pk_bf16_f32 v16, v170, v171
	v_lshlrev_b32_e32 v166, 16, v81
	v_and_b32_e32 v167, 0xffff0000, v81
	v_mul_f32_e32 v168, 0xbfb8aa3b, v166
	v_mul_f32_e32 v169, 0xbfb8aa3b, v167
	v_exp_f32_e32 v168, v168
	v_exp_f32_e32 v169, v169
	v_lshlrev_b32_e32 v170, 16, v17
	v_and_b32_e32 v171, 0xffff0000, v17
	v_add_f32_e32 v168, 1.0, v168
	v_add_f32_e32 v169, 1.0, v169
	v_rcp_f32_e32 v168, v168
	v_rcp_f32_e32 v169, v169
	v_mul_f32_e32 v170, v170, v182
	v_mul_f32_e32 v171, v171, v182
	v_mul_f32_e32 v166, v166, v168
	v_mul_f32_e32 v167, v167, v169
	v_mul_f32_e32 v170, v170, v160
	v_mul_f32_e32 v171, v171, v161
	v_mul_f32_e32 v170, v170, v166
	v_mul_f32_e32 v171, v171, v167
	v_cvt_pk_bf16_f32 v17, v170, v171
	global_load_dwordx4 v[130:133], v1, vcc offset:128
	global_load_dwordx4 v[134:137], v1, vcc offset:144
	global_load_dwordx4 v[138:141], v1, vcc offset:160
	global_load_dwordx4 v[142:145], v1, vcc offset:176
	global_load_dwordx4 v[146:149], v1, vcc offset:192
	global_load_dwordx4 v[150:153], v1, vcc offset:208
	global_load_dwordx4 v[154:157], v1, vcc offset:224
	global_load_dwordx4 v[158:161], v1, vcc offset:240
	s_waitcnt vmcnt(0)
	v_lshlrev_b32_e32 v166, 16, v82
	v_and_b32_e32 v167, 0xffff0000, v82
	v_mul_f32_e32 v168, 0xbfb8aa3b, v166
	v_mul_f32_e32 v169, 0xbfb8aa3b, v167
	v_exp_f32_e32 v168, v168
	v_exp_f32_e32 v169, v169
	v_lshlrev_b32_e32 v170, 16, v18
	v_and_b32_e32 v171, 0xffff0000, v18
	v_add_f32_e32 v168, 1.0, v168
	v_add_f32_e32 v169, 1.0, v169
	v_rcp_f32_e32 v168, v168
	v_rcp_f32_e32 v169, v169
	v_mul_f32_e32 v170, v170, v182
	v_mul_f32_e32 v171, v171, v182
	v_mul_f32_e32 v166, v166, v168
	v_mul_f32_e32 v167, v167, v169
	v_mul_f32_e32 v170, v170, v130
	v_mul_f32_e32 v171, v171, v131
	v_mul_f32_e32 v170, v170, v166
	v_mul_f32_e32 v171, v171, v167
	v_cvt_pk_bf16_f32 v18, v170, v171
	v_lshlrev_b32_e32 v166, 16, v83
	v_and_b32_e32 v167, 0xffff0000, v83
	v_mul_f32_e32 v168, 0xbfb8aa3b, v166
	v_mul_f32_e32 v169, 0xbfb8aa3b, v167
	v_exp_f32_e32 v168, v168
	v_exp_f32_e32 v169, v169
	v_lshlrev_b32_e32 v170, 16, v19
	v_and_b32_e32 v171, 0xffff0000, v19
	v_add_f32_e32 v168, 1.0, v168
	v_add_f32_e32 v169, 1.0, v169
	v_rcp_f32_e32 v168, v168
	v_rcp_f32_e32 v169, v169
	v_mul_f32_e32 v170, v170, v182
	v_mul_f32_e32 v171, v171, v182
	v_mul_f32_e32 v166, v166, v168
	v_mul_f32_e32 v167, v167, v169
	v_mul_f32_e32 v170, v170, v132
	v_mul_f32_e32 v171, v171, v133
	v_mul_f32_e32 v170, v170, v166
	v_mul_f32_e32 v171, v171, v167
	v_cvt_pk_bf16_f32 v19, v170, v171
	v_lshlrev_b32_e32 v166, 16, v84
	v_and_b32_e32 v167, 0xffff0000, v84
	v_mul_f32_e32 v168, 0xbfb8aa3b, v166
	v_mul_f32_e32 v169, 0xbfb8aa3b, v167
	v_exp_f32_e32 v168, v168
	v_exp_f32_e32 v169, v169
	v_lshlrev_b32_e32 v170, 16, v20
	v_and_b32_e32 v171, 0xffff0000, v20
	v_add_f32_e32 v168, 1.0, v168
	v_add_f32_e32 v169, 1.0, v169
	v_rcp_f32_e32 v168, v168
	v_rcp_f32_e32 v169, v169
	v_mul_f32_e32 v170, v170, v182
	v_mul_f32_e32 v171, v171, v182
	v_mul_f32_e32 v166, v166, v168
	v_mul_f32_e32 v167, v167, v169
	v_mul_f32_e32 v170, v170, v134
	v_mul_f32_e32 v171, v171, v135
	v_mul_f32_e32 v170, v170, v166
	v_mul_f32_e32 v171, v171, v167
	v_cvt_pk_bf16_f32 v20, v170, v171
	v_lshlrev_b32_e32 v166, 16, v85
	v_and_b32_e32 v167, 0xffff0000, v85
	v_mul_f32_e32 v168, 0xbfb8aa3b, v166
	v_mul_f32_e32 v169, 0xbfb8aa3b, v167
	v_exp_f32_e32 v168, v168
	v_exp_f32_e32 v169, v169
	v_lshlrev_b32_e32 v170, 16, v21
	v_and_b32_e32 v171, 0xffff0000, v21
	v_add_f32_e32 v168, 1.0, v168
	v_add_f32_e32 v169, 1.0, v169
	v_rcp_f32_e32 v168, v168
	v_rcp_f32_e32 v169, v169
	v_mul_f32_e32 v170, v170, v182
	v_mul_f32_e32 v171, v171, v182
	v_mul_f32_e32 v166, v166, v168
	v_mul_f32_e32 v167, v167, v169
	v_mul_f32_e32 v170, v170, v136
	v_mul_f32_e32 v171, v171, v137
	v_mul_f32_e32 v170, v170, v166
	v_mul_f32_e32 v171, v171, v167
	v_cvt_pk_bf16_f32 v21, v170, v171
	v_lshlrev_b32_e32 v166, 16, v86
	v_and_b32_e32 v167, 0xffff0000, v86
	v_mul_f32_e32 v168, 0xbfb8aa3b, v166
	v_mul_f32_e32 v169, 0xbfb8aa3b, v167
	v_exp_f32_e32 v168, v168
	v_exp_f32_e32 v169, v169
	v_lshlrev_b32_e32 v170, 16, v22
	v_and_b32_e32 v171, 0xffff0000, v22
	v_add_f32_e32 v168, 1.0, v168
	v_add_f32_e32 v169, 1.0, v169
	v_rcp_f32_e32 v168, v168
	v_rcp_f32_e32 v169, v169
	v_mul_f32_e32 v170, v170, v182
	v_mul_f32_e32 v171, v171, v182
	v_mul_f32_e32 v166, v166, v168
	v_mul_f32_e32 v167, v167, v169
	v_mul_f32_e32 v170, v170, v138
	v_mul_f32_e32 v171, v171, v139
	v_mul_f32_e32 v170, v170, v166
	v_mul_f32_e32 v171, v171, v167
	v_cvt_pk_bf16_f32 v22, v170, v171
	v_lshlrev_b32_e32 v166, 16, v87
	v_and_b32_e32 v167, 0xffff0000, v87
	v_mul_f32_e32 v168, 0xbfb8aa3b, v166
	v_mul_f32_e32 v169, 0xbfb8aa3b, v167
	v_exp_f32_e32 v168, v168
	v_exp_f32_e32 v169, v169
	v_lshlrev_b32_e32 v170, 16, v23
	v_and_b32_e32 v171, 0xffff0000, v23
	v_add_f32_e32 v168, 1.0, v168
	v_add_f32_e32 v169, 1.0, v169
	v_rcp_f32_e32 v168, v168
	v_rcp_f32_e32 v169, v169
	v_mul_f32_e32 v170, v170, v182
	v_mul_f32_e32 v171, v171, v182
	v_mul_f32_e32 v166, v166, v168
	v_mul_f32_e32 v167, v167, v169
	v_mul_f32_e32 v170, v170, v140
	v_mul_f32_e32 v171, v171, v141
	v_mul_f32_e32 v170, v170, v166
	v_mul_f32_e32 v171, v171, v167
; DEVI float bflo(unsigned u) { return __uint_as_float(u << 16); }
; DEVI float bfhi(unsigned u) { return __uint_as_float(u & 0xffff0000u); }
; DEVI void gate_phase(const Params& p, int j) {
;     ...
; #pragma unroll
;     for (int q = 0; q < 4; ++q) {
;       const int h = q * 2 + half;
;       const float r = rsqrtf(ss[q] * (1.f / 128.f) + 1e-6f);
;       const float o[4] = {bflo(ov[q].x), bfhi(ov[q].x), bflo(ov[q].y), bfhi(ov[q].y)};
;       const float zz[4] = {bflo(zv[q].x), bfhi(zv[q].x), bflo(zv[q].y), bfhi(zv[q].y)};
;       float y[4];
; #pragma unroll
;       for (int e = 0; e < 4; ++e) y[e] = o[e] * r * w[e] * (zz[e] / (1.f + __expf(-zz[e])));
;       *(u32x2*)(r1 + (size_t)t * 3072 + h * 128 + l31 * 4) = u32x2{pack2(y[0], y[1]), pack2(y[2], y[3])};
	v_cvt_pk_bf16_f32 v23, v170, v171
	v_lshlrev_b32_e32 v166, 16, v88
	v_and_b32_e32 v167, 0xffff0000, v88
	v_mul_f32_e32 v168, 0xbfb8aa3b, v166
	v_mul_f32_e32 v169, 0xbfb8aa3b, v167
	v_exp_f32_e32 v168, v168
	v_exp_f32_e32 v169, v169
	v_lshlrev_b32_e32 v170, 16, v24
	v_and_b32_e32 v171, 0xffff0000, v24
	v_add_f32_e32 v168, 1.0, v168
	v_add_f32_e32 v169, 1.0, v169
	v_rcp_f32_e32 v168, v168
	v_rcp_f32_e32 v169, v169
	v_mul_f32_e32 v170, v170, v182
	v_mul_f32_e32 v171, v171, v182
	v_mul_f32_e32 v166, v166, v168
	v_mul_f32_e32 v167, v167, v169
	v_mul_f32_e32 v170, v170, v142
	v_mul_f32_e32 v171, v171, v143
	v_mul_f32_e32 v170, v170, v166
	v_mul_f32_e32 v171, v171, v167
	v_cvt_pk_bf16_f32 v24, v170, v171
	v_lshlrev_b32_e32 v166, 16, v89
	v_and_b32_e32 v167, 0xffff0000, v89
	v_mul_f32_e32 v168, 0xbfb8aa3b, v166
	v_mul_f32_e32 v169, 0xbfb8aa3b, v167
	v_exp_f32_e32 v168, v168
	v_exp_f32_e32 v169, v169
	v_lshlrev_b32_e32 v170, 16, v25
	v_and_b32_e32 v171, 0xffff0000, v25
	v_add_f32_e32 v168, 1.0, v168
	v_add_f32_e32 v169, 1.0, v169
	v_rcp_f32_e32 v168, v168
	v_rcp_f32_e32 v169, v169
	v_mul_f32_e32 v170, v170, v182
	v_mul_f32_e32 v171, v171, v182
	v_mul_f32_e32 v166, v166, v168
	v_mul_f32_e32 v167, v167, v169
	v_mul_f32_e32 v170, v170, v144
	v_mul_f32_e32 v171, v171, v145
	v_mul_f32_e32 v170, v170, v166
	v_mul_f32_e32 v171, v171, v167
	v_cvt_pk_bf16_f32 v25, v170, v171
	v_lshlrev_b32_e32 v166, 16, v90
	v_and_b32_e32 v167, 0xffff0000, v90
	v_mul_f32_e32 v168, 0xbfb8aa3b, v166
	v_mul_f32_e32 v169, 0xbfb8aa3b, v167
	v_exp_f32_e32 v168, v168
	v_exp_f32_e32 v169, v169
	v_lshlrev_b32_e32 v170, 16, v26
	v_and_b32_e32 v171, 0xffff0000, v26
	v_add_f32_e32 v168, 1.0, v168
	v_add_f32_e32 v169, 1.0, v169
	v_rcp_f32_e32 v168, v168
	v_rcp_f32_e32 v169, v169
	v_mul_f32_e32 v170, v170, v182
	v_mul_f32_e32 v171, v171, v182
	v_mul_f32_e32 v166, v166, v168
	v_mul_f32_e32 v167, v167, v169
	v_mul_f32_e32 v170, v170, v146
	v_mul_f32_e32 v171, v171, v147
	v_mul_f32_e32 v170, v170, v166
	v_mul_f32_e32 v171, v171, v167
	v_cvt_pk_bf16_f32 v26, v170, v171
	v_lshlrev_b32_e32 v166, 16, v91
	v_and_b32_e32 v167, 0xffff0000, v91
	v_mul_f32_e32 v168, 0xbfb8aa3b, v166
	v_mul_f32_e32 v169, 0xbfb8aa3b, v167
	v_exp_f32_e32 v168, v168
	v_exp_f32_e32 v169, v169
	v_lshlrev_b32_e32 v170, 16, v27
	v_and_b32_e32 v171, 0xffff0000, v27
	v_add_f32_e32 v168, 1.0, v168
	v_add_f32_e32 v169, 1.0, v169
	v_rcp_f32_e32 v168, v168
	v_rcp_f32_e32 v169, v169
	v_mul_f32_e32 v170, v170, v182
	v_mul_f32_e32 v171, v171, v182
	v_mul_f32_e32 v166, v166, v168
	v_mul_f32_e32 v167, v167, v169
	v_mul_f32_e32 v170, v170, v148
	v_mul_f32_e32 v171, v171, v149
	v_mul_f32_e32 v170, v170, v166
	v_mul_f32_e32 v171, v171, v167
	v_cvt_pk_bf16_f32 v27, v170, v171
	v_lshlrev_b32_e32 v166, 16, v92
	v_and_b32_e32 v167, 0xffff0000, v92
	v_mul_f32_e32 v168, 0xbfb8aa3b, v166
	v_mul_f32_e32 v169, 0xbfb8aa3b, v167
	v_exp_f32_e32 v168, v168
	v_exp_f32_e32 v169, v169
	v_lshlrev_b32_e32 v170, 16, v28
	v_and_b32_e32 v171, 0xffff0000, v28
	v_add_f32_e32 v168, 1.0, v168
	v_add_f32_e32 v169, 1.0, v169
	v_rcp_f32_e32 v168, v168
	v_rcp_f32_e32 v169, v169
	v_mul_f32_e32 v170, v170, v182
	v_mul_f32_e32 v171, v171, v182
	v_mul_f32_e32 v166, v166, v168
	v_mul_f32_e32 v167, v167, v169
	v_mul_f32_e32 v170, v170, v150
	v_mul_f32_e32 v171, v171, v151
	v_mul_f32_e32 v170, v170, v166
	v_mul_f32_e32 v171, v171, v167
	v_cvt_pk_bf16_f32 v28, v170, v171
	v_lshlrev_b32_e32 v166, 16, v93
	v_and_b32_e32 v167, 0xffff0000, v93
	v_mul_f32_e32 v168, 0xbfb8aa3b, v166
	v_mul_f32_e32 v169, 0xbfb8aa3b, v167
	v_exp_f32_e32 v168, v168
	v_exp_f32_e32 v169, v169
	v_lshlrev_b32_e32 v170, 16, v29
	v_and_b32_e32 v171, 0xffff0000, v29
	v_add_f32_e32 v168, 1.0, v168
	v_add_f32_e32 v169, 1.0, v169
	v_rcp_f32_e32 v168, v168
	v_rcp_f32_e32 v169, v169
	v_mul_f32_e32 v170, v170, v182
	v_mul_f32_e32 v171, v171, v182
	v_mul_f32_e32 v166, v166, v168
	v_mul_f32_e32 v167, v167, v169
	v_mul_f32_e32 v170, v170, v152
	v_mul_f32_e32 v171, v171, v153
	v_mul_f32_e32 v170, v170, v166
	v_mul_f32_e32 v171, v171, v167
	v_cvt_pk_bf16_f32 v29, v170, v171
	v_lshlrev_b32_e32 v166, 16, v94
	v_and_b32_e32 v167, 0xffff0000, v94
	v_mul_f32_e32 v168, 0xbfb8aa3b, v166
	v_mul_f32_e32 v169, 0xbfb8aa3b, v167
	v_exp_f32_e32 v168, v168
	v_exp_f32_e32 v169, v169
	v_lshlrev_b32_e32 v170, 16, v30
	v_and_b32_e32 v171, 0xffff0000, v30
	v_add_f32_e32 v168, 1.0, v168
	v_add_f32_e32 v169, 1.0, v169
	v_rcp_f32_e32 v168, v168
	v_rcp_f32_e32 v169, v169
	v_mul_f32_e32 v170, v170, v182
	v_mul_f32_e32 v171, v171, v182
	v_mul_f32_e32 v166, v166, v168
	v_mul_f32_e32 v167, v167, v169
	v_mul_f32_e32 v170, v170, v154
	v_mul_f32_e32 v171, v171, v155
	v_mul_f32_e32 v170, v170, v166
	v_mul_f32_e32 v171, v171, v167
	v_cvt_pk_bf16_f32 v30, v170, v171
	v_lshlrev_b32_e32 v166, 16, v95
	v_and_b32_e32 v167, 0xffff0000, v95
	v_mul_f32_e32 v168, 0xbfb8aa3b, v166
	v_mul_f32_e32 v169, 0xbfb8aa3b, v167
	v_exp_f32_e32 v168, v168
	v_exp_f32_e32 v169, v169
	v_lshlrev_b32_e32 v170, 16, v31
	v_and_b32_e32 v171, 0xffff0000, v31
	v_add_f32_e32 v168, 1.0, v168
	v_add_f32_e32 v169, 1.0, v169
	v_rcp_f32_e32 v168, v168
	v_rcp_f32_e32 v169, v169
	v_mul_f32_e32 v170, v170, v182
	v_mul_f32_e32 v171, v171, v182
	v_mul_f32_e32 v166, v166, v168
	v_mul_f32_e32 v167, v167, v169
	v_mul_f32_e32 v170, v170, v156
	v_mul_f32_e32 v171, v171, v157
	v_mul_f32_e32 v170, v170, v166
	v_mul_f32_e32 v171, v171, v167
	v_cvt_pk_bf16_f32 v31, v170, v171
	v_lshlrev_b32_e32 v166, 16, v96
	v_and_b32_e32 v167, 0xffff0000, v96
	v_mul_f32_e32 v168, 0xbfb8aa3b, v166
	v_mul_f32_e32 v169, 0xbfb8aa3b, v167
	v_exp_f32_e32 v168, v168
	v_exp_f32_e32 v169, v169
	v_lshlrev_b32_e32 v170, 16, v32
; DEVI float bflo(unsigned u) { return __uint_as_float(u << 16); }
; DEVI float bfhi(unsigned u) { return __uint_as_float(u & 0xffff0000u); }
; DEVI void gate_phase(const Params& p, int j) {
;     ...
;   const f32x4 w = *(const f32x4*)(nw + l31 * 4);
;     ...
; #pragma unroll
;     for (int q = 0; q < 4; ++q) {
;       const int h = q * 2 + half;
;       const float r = rsqrtf(ss[q] * (1.f / 128.f) + 1e-6f);
;       const float o[4] = {bflo(ov[q].x), bfhi(ov[q].x), bflo(ov[q].y), bfhi(ov[q].y)};
;       const float zz[4] = {bflo(zv[q].x), bfhi(zv[q].x), bflo(zv[q].y), bfhi(zv[q].y)};
;       float y[4];
; #pragma unroll
;       for (int e = 0; e < 4; ++e) y[e] = o[e] * r * w[e] * (zz[e] / (1.f + __expf(-zz[e])));
;       *(u32x2*)(r1 + (size_t)t * 3072 + h * 128 + l31 * 4) = u32x2{pack2(y[0], y[1]), pack2(y[2], y[3])};
	v_and_b32_e32 v171, 0xffff0000, v32
	v_add_f32_e32 v168, 1.0, v168
	v_add_f32_e32 v169, 1.0, v169
	v_rcp_f32_e32 v168, v168
	v_rcp_f32_e32 v169, v169
	v_mul_f32_e32 v170, v170, v182
	v_mul_f32_e32 v171, v171, v182
	v_mul_f32_e32 v166, v166, v168
	v_mul_f32_e32 v167, v167, v169
	v_mul_f32_e32 v170, v170, v158
	v_mul_f32_e32 v171, v171, v159
	v_mul_f32_e32 v170, v170, v166
	v_mul_f32_e32 v171, v171, v167
	v_cvt_pk_bf16_f32 v32, v170, v171
	v_lshlrev_b32_e32 v166, 16, v97
	v_and_b32_e32 v167, 0xffff0000, v97
	v_mul_f32_e32 v168, 0xbfb8aa3b, v166
	v_mul_f32_e32 v169, 0xbfb8aa3b, v167
	v_exp_f32_e32 v168, v168
	v_exp_f32_e32 v169, v169
	v_lshlrev_b32_e32 v170, 16, v33
	v_and_b32_e32 v171, 0xffff0000, v33
	v_add_f32_e32 v168, 1.0, v168
	v_add_f32_e32 v169, 1.0, v169
	v_rcp_f32_e32 v168, v168
	v_rcp_f32_e32 v169, v169
	v_mul_f32_e32 v170, v170, v182
	v_mul_f32_e32 v171, v171, v182
	v_mul_f32_e32 v166, v166, v168
	v_mul_f32_e32 v167, v167, v169
	v_mul_f32_e32 v170, v170, v160
	v_mul_f32_e32 v171, v171, v161
	v_mul_f32_e32 v170, v170, v166
	v_mul_f32_e32 v171, v171, v167
	v_cvt_pk_bf16_f32 v33, v170, v171
	global_load_dwordx4 v[130:133], v1, vcc offset:256
	global_load_dwordx4 v[134:137], v1, vcc offset:272
	global_load_dwordx4 v[138:141], v1, vcc offset:288
	global_load_dwordx4 v[142:145], v1, vcc offset:304
	global_load_dwordx4 v[146:149], v1, vcc offset:320
	global_load_dwordx4 v[150:153], v1, vcc offset:336
	global_load_dwordx4 v[154:157], v1, vcc offset:352
	global_load_dwordx4 v[158:161], v1, vcc offset:368
	s_waitcnt vmcnt(0)
	v_lshlrev_b32_e32 v166, 16, v98
	v_and_b32_e32 v167, 0xffff0000, v98
	v_mul_f32_e32 v168, 0xbfb8aa3b, v166
	v_mul_f32_e32 v169, 0xbfb8aa3b, v167
	v_exp_f32_e32 v168, v168
	v_exp_f32_e32 v169, v169
	v_lshlrev_b32_e32 v170, 16, v34
	v_and_b32_e32 v171, 0xffff0000, v34
	v_add_f32_e32 v168, 1.0, v168
	v_add_f32_e32 v169, 1.0, v169
	v_rcp_f32_e32 v168, v168
	v_rcp_f32_e32 v169, v169
	v_mul_f32_e32 v170, v170, v182
	v_mul_f32_e32 v171, v171, v182
	v_mul_f32_e32 v166, v166, v168
	v_mul_f32_e32 v167, v167, v169
	v_mul_f32_e32 v170, v170, v130
	v_mul_f32_e32 v171, v171, v131
	v_mul_f32_e32 v170, v170, v166
	v_mul_f32_e32 v171, v171, v167
	v_cvt_pk_bf16_f32 v34, v170, v171
	v_lshlrev_b32_e32 v166, 16, v99
	v_and_b32_e32 v167, 0xffff0000, v99
	v_mul_f32_e32 v168, 0xbfb8aa3b, v166
	v_mul_f32_e32 v169, 0xbfb8aa3b, v167
	v_exp_f32_e32 v168, v168
	v_exp_f32_e32 v169, v169
	v_lshlrev_b32_e32 v170, 16, v35
	v_and_b32_e32 v171, 0xffff0000, v35
	v_add_f32_e32 v168, 1.0, v168
	v_add_f32_e32 v169, 1.0, v169
	v_rcp_f32_e32 v168, v168
	v_rcp_f32_e32 v169, v169
	v_mul_f32_e32 v170, v170, v182
	v_mul_f32_e32 v171, v171, v182
	v_mul_f32_e32 v166, v166, v168
	v_mul_f32_e32 v167, v167, v169
	v_mul_f32_e32 v170, v170, v132
	v_mul_f32_e32 v171, v171, v133
	v_mul_f32_e32 v170, v170, v166
	v_mul_f32_e32 v171, v171, v167
	v_cvt_pk_bf16_f32 v35, v170, v171
	v_lshlrev_b32_e32 v166, 16, v100
	v_and_b32_e32 v167, 0xffff0000, v100
	v_mul_f32_e32 v168, 0xbfb8aa3b, v166
	v_mul_f32_e32 v169, 0xbfb8aa3b, v167
	v_exp_f32_e32 v168, v168
	v_exp_f32_e32 v169, v169
	v_lshlrev_b32_e32 v170, 16, v36
	v_and_b32_e32 v171, 0xffff0000, v36
	v_add_f32_e32 v168, 1.0, v168
	v_add_f32_e32 v169, 1.0, v169
	v_rcp_f32_e32 v168, v168
	v_rcp_f32_e32 v169, v169
	v_mul_f32_e32 v170, v170, v182
	v_mul_f32_e32 v171, v171, v182
	v_mul_f32_e32 v166, v166, v168
	v_mul_f32_e32 v167, v167, v169
	v_mul_f32_e32 v170, v170, v134
	v_mul_f32_e32 v171, v171, v135
	v_mul_f32_e32 v170, v170, v166
	v_mul_f32_e32 v171, v171, v167
	v_cvt_pk_bf16_f32 v36, v170, v171
	v_lshlrev_b32_e32 v166, 16, v101
	v_and_b32_e32 v167, 0xffff0000, v101
	v_mul_f32_e32 v168, 0xbfb8aa3b, v166
	v_mul_f32_e32 v169, 0xbfb8aa3b, v167
	v_exp_f32_e32 v168, v168
	v_exp_f32_e32 v169, v169
	v_lshlrev_b32_e32 v170, 16, v37
	v_and_b32_e32 v171, 0xffff0000, v37
	v_add_f32_e32 v168, 1.0, v168
	v_add_f32_e32 v169, 1.0, v169
	v_rcp_f32_e32 v168, v168
	v_rcp_f32_e32 v169, v169
	v_mul_f32_e32 v170, v170, v182
	v_mul_f32_e32 v171, v171, v182
	v_mul_f32_e32 v166, v166, v168
	v_mul_f32_e32 v167, v167, v169
	v_mul_f32_e32 v170, v170, v136
	v_mul_f32_e32 v171, v171, v137
	v_mul_f32_e32 v170, v170, v166
	v_mul_f32_e32 v171, v171, v167
	v_cvt_pk_bf16_f32 v37, v170, v171
	v_lshlrev_b32_e32 v166, 16, v102
	v_and_b32_e32 v167, 0xffff0000, v102
	v_mul_f32_e32 v168, 0xbfb8aa3b, v166
	v_mul_f32_e32 v169, 0xbfb8aa3b, v167
	v_exp_f32_e32 v168, v168
	v_exp_f32_e32 v169, v169
	v_lshlrev_b32_e32 v170, 16, v38
	v_and_b32_e32 v171, 0xffff0000, v38
	v_add_f32_e32 v168, 1.0, v168
	v_add_f32_e32 v169, 1.0, v169
	v_rcp_f32_e32 v168, v168
	v_rcp_f32_e32 v169, v169
	v_mul_f32_e32 v170, v170, v182
	v_mul_f32_e32 v171, v171, v182
	v_mul_f32_e32 v166, v166, v168
	v_mul_f32_e32 v167, v167, v169
	v_mul_f32_e32 v170, v170, v138
	v_mul_f32_e32 v171, v171, v139
	v_mul_f32_e32 v170, v170, v166
	v_mul_f32_e32 v171, v171, v167
	v_cvt_pk_bf16_f32 v38, v170, v171
	v_lshlrev_b32_e32 v166, 16, v103
	v_and_b32_e32 v167, 0xffff0000, v103
	v_mul_f32_e32 v168, 0xbfb8aa3b, v166
	v_mul_f32_e32 v169, 0xbfb8aa3b, v167
	v_exp_f32_e32 v168, v168
	v_exp_f32_e32 v169, v169
	v_lshlrev_b32_e32 v170, 16, v39
	v_and_b32_e32 v171, 0xffff0000, v39
	v_add_f32_e32 v168, 1.0, v168
	v_add_f32_e32 v169, 1.0, v169
	v_rcp_f32_e32 v168, v168
	v_rcp_f32_e32 v169, v169
	v_mul_f32_e32 v170, v170, v182
	v_mul_f32_e32 v171, v171, v182
	v_mul_f32_e32 v166, v166, v168
	v_mul_f32_e32 v167, v167, v169
	v_mul_f32_e32 v170, v170, v140
	v_mul_f32_e32 v171, v171, v141
	v_mul_f32_e32 v170, v170, v166
	v_mul_f32_e32 v171, v171, v167
	v_cvt_pk_bf16_f32 v39, v170, v171
	v_lshlrev_b32_e32 v166, 16, v104
; DEVI float bflo(unsigned u) { return __uint_as_float(u << 16); }
; DEVI float bfhi(unsigned u) { return __uint_as_float(u & 0xffff0000u); }
; DEVI void gate_phase(const Params& p, int j) {
;     ...
; #pragma unroll
;     for (int q = 0; q < 4; ++q) {
;       const int h = q * 2 + half;
;       const float r = rsqrtf(ss[q] * (1.f / 128.f) + 1e-6f);
;       const float o[4] = {bflo(ov[q].x), bfhi(ov[q].x), bflo(ov[q].y), bfhi(ov[q].y)};
;       const float zz[4] = {bflo(zv[q].x), bfhi(zv[q].x), bflo(zv[q].y), bfhi(zv[q].y)};
;       float y[4];
; #pragma unroll
;       for (int e = 0; e < 4; ++e) y[e] = o[e] * r * w[e] * (zz[e] / (1.f + __expf(-zz[e])));
;       *(u32x2*)(r1 + (size_t)t * 3072 + h * 128 + l31 * 4) = u32x2{pack2(y[0], y[1]), pack2(y[2], y[3])};
	v_and_b32_e32 v167, 0xffff0000, v104
	v_mul_f32_e32 v168, 0xbfb8aa3b, v166
	v_mul_f32_e32 v169, 0xbfb8aa3b, v167
	v_exp_f32_e32 v168, v168
	v_exp_f32_e32 v169, v169
	v_lshlrev_b32_e32 v170, 16, v40
	v_and_b32_e32 v171, 0xffff0000, v40
	v_add_f32_e32 v168, 1.0, v168
	v_add_f32_e32 v169, 1.0, v169
	v_rcp_f32_e32 v168, v168
	v_rcp_f32_e32 v169, v169
	v_mul_f32_e32 v170, v170, v182
	v_mul_f32_e32 v171, v171, v182
	v_mul_f32_e32 v166, v166, v168
	v_mul_f32_e32 v167, v167, v169
	v_mul_f32_e32 v170, v170, v142
	v_mul_f32_e32 v171, v171, v143
	v_mul_f32_e32 v170, v170, v166
	v_mul_f32_e32 v171, v171, v167
	v_cvt_pk_bf16_f32 v40, v170, v171
	v_lshlrev_b32_e32 v166, 16, v105
	v_and_b32_e32 v167, 0xffff0000, v105
	v_mul_f32_e32 v168, 0xbfb8aa3b, v166
	v_mul_f32_e32 v169, 0xbfb8aa3b, v167
	v_exp_f32_e32 v168, v168
	v_exp_f32_e32 v169, v169
	v_lshlrev_b32_e32 v170, 16, v41
	v_and_b32_e32 v171, 0xffff0000, v41
	v_add_f32_e32 v168, 1.0, v168
	v_add_f32_e32 v169, 1.0, v169
	v_rcp_f32_e32 v168, v168
	v_rcp_f32_e32 v169, v169
	v_mul_f32_e32 v170, v170, v182
	v_mul_f32_e32 v171, v171, v182
	v_mul_f32_e32 v166, v166, v168
	v_mul_f32_e32 v167, v167, v169
	v_mul_f32_e32 v170, v170, v144
	v_mul_f32_e32 v171, v171, v145
	v_mul_f32_e32 v170, v170, v166
	v_mul_f32_e32 v171, v171, v167
	v_cvt_pk_bf16_f32 v41, v170, v171
	v_lshlrev_b32_e32 v166, 16, v106
	v_and_b32_e32 v167, 0xffff0000, v106
	v_mul_f32_e32 v168, 0xbfb8aa3b, v166
	v_mul_f32_e32 v169, 0xbfb8aa3b, v167
	v_exp_f32_e32 v168, v168
	v_exp_f32_e32 v169, v169
	v_lshlrev_b32_e32 v170, 16, v42
	v_and_b32_e32 v171, 0xffff0000, v42
	v_add_f32_e32 v168, 1.0, v168
	v_add_f32_e32 v169, 1.0, v169
	v_rcp_f32_e32 v168, v168
	v_rcp_f32_e32 v169, v169
	v_mul_f32_e32 v170, v170, v182
	v_mul_f32_e32 v171, v171, v182
	v_mul_f32_e32 v166, v166, v168
	v_mul_f32_e32 v167, v167, v169
	v_mul_f32_e32 v170, v170, v146
	v_mul_f32_e32 v171, v171, v147
	v_mul_f32_e32 v170, v170, v166
	v_mul_f32_e32 v171, v171, v167
	v_cvt_pk_bf16_f32 v42, v170, v171
	v_lshlrev_b32_e32 v166, 16, v107
	v_and_b32_e32 v167, 0xffff0000, v107
	v_mul_f32_e32 v168, 0xbfb8aa3b, v166
	v_mul_f32_e32 v169, 0xbfb8aa3b, v167
	v_exp_f32_e32 v168, v168
	v_exp_f32_e32 v169, v169
	v_lshlrev_b32_e32 v170, 16, v43
	v_and_b32_e32 v171, 0xffff0000, v43
	v_add_f32_e32 v168, 1.0, v168
	v_add_f32_e32 v169, 1.0, v169
	v_rcp_f32_e32 v168, v168
	v_rcp_f32_e32 v169, v169
	v_mul_f32_e32 v170, v170, v182
	v_mul_f32_e32 v171, v171, v182
	v_mul_f32_e32 v166, v166, v168
	v_mul_f32_e32 v167, v167, v169
	v_mul_f32_e32 v170, v170, v148
	v_mul_f32_e32 v171, v171, v149
	v_mul_f32_e32 v170, v170, v166
	v_mul_f32_e32 v171, v171, v167
	v_cvt_pk_bf16_f32 v43, v170, v171
	v_lshlrev_b32_e32 v166, 16, v108
	v_and_b32_e32 v167, 0xffff0000, v108
	v_mul_f32_e32 v168, 0xbfb8aa3b, v166
	v_mul_f32_e32 v169, 0xbfb8aa3b, v167
	v_exp_f32_e32 v168, v168
	v_exp_f32_e32 v169, v169
	v_lshlrev_b32_e32 v170, 16, v44
	v_and_b32_e32 v171, 0xffff0000, v44
	v_add_f32_e32 v168, 1.0, v168
	v_add_f32_e32 v169, 1.0, v169
	v_rcp_f32_e32 v168, v168
	v_rcp_f32_e32 v169, v169
	v_mul_f32_e32 v170, v170, v182
	v_mul_f32_e32 v171, v171, v182
	v_mul_f32_e32 v166, v166, v168
	v_mul_f32_e32 v167, v167, v169
	v_mul_f32_e32 v170, v170, v150
	v_mul_f32_e32 v171, v171, v151
	v_mul_f32_e32 v170, v170, v166
	v_mul_f32_e32 v171, v171, v167
	v_cvt_pk_bf16_f32 v44, v170, v171
	v_lshlrev_b32_e32 v166, 16, v109
	v_and_b32_e32 v167, 0xffff0000, v109
	v_mul_f32_e32 v168, 0xbfb8aa3b, v166
	v_mul_f32_e32 v169, 0xbfb8aa3b, v167
	v_exp_f32_e32 v168, v168
	v_exp_f32_e32 v169, v169
	v_lshlrev_b32_e32 v170, 16, v45
	v_and_b32_e32 v171, 0xffff0000, v45
	v_add_f32_e32 v168, 1.0, v168
	v_add_f32_e32 v169, 1.0, v169
	v_rcp_f32_e32 v168, v168
	v_rcp_f32_e32 v169, v169
	v_mul_f32_e32 v170, v170, v182
	v_mul_f32_e32 v171, v171, v182
	v_mul_f32_e32 v166, v166, v168
	v_mul_f32_e32 v167, v167, v169
	v_mul_f32_e32 v170, v170, v152
	v_mul_f32_e32 v171, v171, v153
	v_mul_f32_e32 v170, v170, v166
	v_mul_f32_e32 v171, v171, v167
	v_cvt_pk_bf16_f32 v45, v170, v171
	v_lshlrev_b32_e32 v166, 16, v110
	v_and_b32_e32 v167, 0xffff0000, v110
	v_mul_f32_e32 v168, 0xbfb8aa3b, v166
	v_mul_f32_e32 v169, 0xbfb8aa3b, v167
	v_exp_f32_e32 v168, v168
	v_exp_f32_e32 v169, v169
	v_lshlrev_b32_e32 v170, 16, v46
	v_and_b32_e32 v171, 0xffff0000, v46
	v_add_f32_e32 v168, 1.0, v168
	v_add_f32_e32 v169, 1.0, v169
	v_rcp_f32_e32 v168, v168
	v_rcp_f32_e32 v169, v169
	v_mul_f32_e32 v170, v170, v182
	v_mul_f32_e32 v171, v171, v182
	v_mul_f32_e32 v166, v166, v168
	v_mul_f32_e32 v167, v167, v169
	v_mul_f32_e32 v170, v170, v154
	v_mul_f32_e32 v171, v171, v155
	v_mul_f32_e32 v170, v170, v166
	v_mul_f32_e32 v171, v171, v167
	v_cvt_pk_bf16_f32 v46, v170, v171
	v_lshlrev_b32_e32 v166, 16, v111
	v_and_b32_e32 v167, 0xffff0000, v111
	v_mul_f32_e32 v168, 0xbfb8aa3b, v166
	v_mul_f32_e32 v169, 0xbfb8aa3b, v167
	v_exp_f32_e32 v168, v168
	v_exp_f32_e32 v169, v169
	v_lshlrev_b32_e32 v170, 16, v47
	v_and_b32_e32 v171, 0xffff0000, v47
	v_add_f32_e32 v168, 1.0, v168
	v_add_f32_e32 v169, 1.0, v169
	v_rcp_f32_e32 v168, v168
	v_rcp_f32_e32 v169, v169
	v_mul_f32_e32 v170, v170, v182
	v_mul_f32_e32 v171, v171, v182
	v_mul_f32_e32 v166, v166, v168
	v_mul_f32_e32 v167, v167, v169
	v_mul_f32_e32 v170, v170, v156
	v_mul_f32_e32 v171, v171, v157
	v_mul_f32_e32 v170, v170, v166
	v_mul_f32_e32 v171, v171, v167
	v_cvt_pk_bf16_f32 v47, v170, v171
	v_lshlrev_b32_e32 v166, 16, v112
	v_and_b32_e32 v167, 0xffff0000, v112
	v_mul_f32_e32 v168, 0xbfb8aa3b, v166
	v_mul_f32_e32 v169, 0xbfb8aa3b, v167
	v_exp_f32_e32 v168, v168
	v_exp_f32_e32 v169, v169
	v_lshlrev_b32_e32 v170, 16, v48
	v_and_b32_e32 v171, 0xffff0000, v48
; DEVI float bflo(unsigned u) { return __uint_as_float(u << 16); }
; DEVI float bfhi(unsigned u) { return __uint_as_float(u & 0xffff0000u); }
; DEVI void gate_phase(const Params& p, int j) {
;     ...
;   const f32x4 w = *(const f32x4*)(nw + l31 * 4);
;     ...
; #pragma unroll
;     for (int q = 0; q < 4; ++q) {
;       const int h = q * 2 + half;
;       const float r = rsqrtf(ss[q] * (1.f / 128.f) + 1e-6f);
;       const float o[4] = {bflo(ov[q].x), bfhi(ov[q].x), bflo(ov[q].y), bfhi(ov[q].y)};
;       const float zz[4] = {bflo(zv[q].x), bfhi(zv[q].x), bflo(zv[q].y), bfhi(zv[q].y)};
;       float y[4];
; #pragma unroll
;       for (int e = 0; e < 4; ++e) y[e] = o[e] * r * w[e] * (zz[e] / (1.f + __expf(-zz[e])));
;       *(u32x2*)(r1 + (size_t)t * 3072 + h * 128 + l31 * 4) = u32x2{pack2(y[0], y[1]), pack2(y[2], y[3])};
	v_add_f32_e32 v168, 1.0, v168
	v_add_f32_e32 v169, 1.0, v169
	v_rcp_f32_e32 v168, v168
	v_rcp_f32_e32 v169, v169
	v_mul_f32_e32 v170, v170, v182
	v_mul_f32_e32 v171, v171, v182
	v_mul_f32_e32 v166, v166, v168
	v_mul_f32_e32 v167, v167, v169
	v_mul_f32_e32 v170, v170, v158
	v_mul_f32_e32 v171, v171, v159
	v_mul_f32_e32 v170, v170, v166
	v_mul_f32_e32 v171, v171, v167
	v_cvt_pk_bf16_f32 v48, v170, v171
	v_lshlrev_b32_e32 v166, 16, v113
	v_and_b32_e32 v167, 0xffff0000, v113
	v_mul_f32_e32 v168, 0xbfb8aa3b, v166
	v_mul_f32_e32 v169, 0xbfb8aa3b, v167
	v_exp_f32_e32 v168, v168
	v_exp_f32_e32 v169, v169
	v_lshlrev_b32_e32 v170, 16, v49
	v_and_b32_e32 v171, 0xffff0000, v49
	v_add_f32_e32 v168, 1.0, v168
	v_add_f32_e32 v169, 1.0, v169
	v_rcp_f32_e32 v168, v168
	v_rcp_f32_e32 v169, v169
	v_mul_f32_e32 v170, v170, v182
	v_mul_f32_e32 v171, v171, v182
	v_mul_f32_e32 v166, v166, v168
	v_mul_f32_e32 v167, v167, v169
	v_mul_f32_e32 v170, v170, v160
	v_mul_f32_e32 v171, v171, v161
	v_mul_f32_e32 v170, v170, v166
	v_mul_f32_e32 v171, v171, v167
	v_cvt_pk_bf16_f32 v49, v170, v171
	global_load_dwordx4 v[130:133], v1, vcc offset:384
	global_load_dwordx4 v[134:137], v1, vcc offset:400
	global_load_dwordx4 v[138:141], v1, vcc offset:416
	global_load_dwordx4 v[142:145], v1, vcc offset:432
	global_load_dwordx4 v[146:149], v1, vcc offset:448
	global_load_dwordx4 v[150:153], v1, vcc offset:464
	global_load_dwordx4 v[154:157], v1, vcc offset:480
	global_load_dwordx4 v[158:161], v1, vcc offset:496
	s_waitcnt vmcnt(0)
	v_lshlrev_b32_e32 v166, 16, v114
	v_and_b32_e32 v167, 0xffff0000, v114
	v_mul_f32_e32 v168, 0xbfb8aa3b, v166
	v_mul_f32_e32 v169, 0xbfb8aa3b, v167
	v_exp_f32_e32 v168, v168
	v_exp_f32_e32 v169, v169
	v_lshlrev_b32_e32 v170, 16, v50
	v_and_b32_e32 v171, 0xffff0000, v50
	v_add_f32_e32 v168, 1.0, v168
	v_add_f32_e32 v169, 1.0, v169
	v_rcp_f32_e32 v168, v168
	v_rcp_f32_e32 v169, v169
	v_mul_f32_e32 v170, v170, v182
	v_mul_f32_e32 v171, v171, v182
	v_mul_f32_e32 v166, v166, v168
	v_mul_f32_e32 v167, v167, v169
	v_mul_f32_e32 v170, v170, v130
	v_mul_f32_e32 v171, v171, v131
	v_mul_f32_e32 v170, v170, v166
	v_mul_f32_e32 v171, v171, v167
	v_cvt_pk_bf16_f32 v50, v170, v171
	v_lshlrev_b32_e32 v166, 16, v115
	v_and_b32_e32 v167, 0xffff0000, v115
	v_mul_f32_e32 v168, 0xbfb8aa3b, v166
	v_mul_f32_e32 v169, 0xbfb8aa3b, v167
	v_exp_f32_e32 v168, v168
	v_exp_f32_e32 v169, v169
	v_lshlrev_b32_e32 v170, 16, v51
	v_and_b32_e32 v171, 0xffff0000, v51
	v_add_f32_e32 v168, 1.0, v168
	v_add_f32_e32 v169, 1.0, v169
	v_rcp_f32_e32 v168, v168
	v_rcp_f32_e32 v169, v169
	v_mul_f32_e32 v170, v170, v182
	v_mul_f32_e32 v171, v171, v182
	v_mul_f32_e32 v166, v166, v168
	v_mul_f32_e32 v167, v167, v169
	v_mul_f32_e32 v170, v170, v132
	v_mul_f32_e32 v171, v171, v133
	v_mul_f32_e32 v170, v170, v166
	v_mul_f32_e32 v171, v171, v167
	v_cvt_pk_bf16_f32 v51, v170, v171
	v_lshlrev_b32_e32 v166, 16, v116
	v_and_b32_e32 v167, 0xffff0000, v116
	v_mul_f32_e32 v168, 0xbfb8aa3b, v166
	v_mul_f32_e32 v169, 0xbfb8aa3b, v167
	v_exp_f32_e32 v168, v168
	v_exp_f32_e32 v169, v169
	v_lshlrev_b32_e32 v170, 16, v52
	v_and_b32_e32 v171, 0xffff0000, v52
	v_add_f32_e32 v168, 1.0, v168
	v_add_f32_e32 v169, 1.0, v169
	v_rcp_f32_e32 v168, v168
	v_rcp_f32_e32 v169, v169
	v_mul_f32_e32 v170, v170, v182
	v_mul_f32_e32 v171, v171, v182
	v_mul_f32_e32 v166, v166, v168
	v_mul_f32_e32 v167, v167, v169
	v_mul_f32_e32 v170, v170, v134
	v_mul_f32_e32 v171, v171, v135
	v_mul_f32_e32 v170, v170, v166
	v_mul_f32_e32 v171, v171, v167
	v_cvt_pk_bf16_f32 v52, v170, v171
	v_lshlrev_b32_e32 v166, 16, v117
	v_and_b32_e32 v167, 0xffff0000, v117
	v_mul_f32_e32 v168, 0xbfb8aa3b, v166
	v_mul_f32_e32 v169, 0xbfb8aa3b, v167
	v_exp_f32_e32 v168, v168
	v_exp_f32_e32 v169, v169
	v_lshlrev_b32_e32 v170, 16, v53
	v_and_b32_e32 v171, 0xffff0000, v53
	v_add_f32_e32 v168, 1.0, v168
	v_add_f32_e32 v169, 1.0, v169
	v_rcp_f32_e32 v168, v168
	v_rcp_f32_e32 v169, v169
	v_mul_f32_e32 v170, v170, v182
	v_mul_f32_e32 v171, v171, v182
	v_mul_f32_e32 v166, v166, v168
	v_mul_f32_e32 v167, v167, v169
	v_mul_f32_e32 v170, v170, v136
	v_mul_f32_e32 v171, v171, v137
	v_mul_f32_e32 v170, v170, v166
	v_mul_f32_e32 v171, v171, v167
	v_cvt_pk_bf16_f32 v53, v170, v171
	v_lshlrev_b32_e32 v166, 16, v118
	v_and_b32_e32 v167, 0xffff0000, v118
	v_mul_f32_e32 v168, 0xbfb8aa3b, v166
	v_mul_f32_e32 v169, 0xbfb8aa3b, v167
	v_exp_f32_e32 v168, v168
	v_exp_f32_e32 v169, v169
	v_lshlrev_b32_e32 v170, 16, v54
	v_and_b32_e32 v171, 0xffff0000, v54
	v_add_f32_e32 v168, 1.0, v168
	v_add_f32_e32 v169, 1.0, v169
	v_rcp_f32_e32 v168, v168
	v_rcp_f32_e32 v169, v169
	v_mul_f32_e32 v170, v170, v182
	v_mul_f32_e32 v171, v171, v182
	v_mul_f32_e32 v166, v166, v168
	v_mul_f32_e32 v167, v167, v169
	v_mul_f32_e32 v170, v170, v138
	v_mul_f32_e32 v171, v171, v139
	v_mul_f32_e32 v170, v170, v166
	v_mul_f32_e32 v171, v171, v167
	v_cvt_pk_bf16_f32 v54, v170, v171
	v_lshlrev_b32_e32 v166, 16, v119
	v_and_b32_e32 v167, 0xffff0000, v119
	v_mul_f32_e32 v168, 0xbfb8aa3b, v166
	v_mul_f32_e32 v169, 0xbfb8aa3b, v167
	v_exp_f32_e32 v168, v168
	v_exp_f32_e32 v169, v169
	v_lshlrev_b32_e32 v170, 16, v55
	v_and_b32_e32 v171, 0xffff0000, v55
	v_add_f32_e32 v168, 1.0, v168
	v_add_f32_e32 v169, 1.0, v169
	v_rcp_f32_e32 v168, v168
	v_rcp_f32_e32 v169, v169
	v_mul_f32_e32 v170, v170, v182
	v_mul_f32_e32 v171, v171, v182
	v_mul_f32_e32 v166, v166, v168
	v_mul_f32_e32 v167, v167, v169
	v_mul_f32_e32 v170, v170, v140
	v_mul_f32_e32 v171, v171, v141
	v_mul_f32_e32 v170, v170, v166
	v_mul_f32_e32 v171, v171, v167
	v_cvt_pk_bf16_f32 v55, v170, v171
	v_lshlrev_b32_e32 v166, 16, v120
	v_and_b32_e32 v167, 0xffff0000, v120
; DEVI float bflo(unsigned u) { return __uint_as_float(u << 16); }
; DEVI float bfhi(unsigned u) { return __uint_as_float(u & 0xffff0000u); }
; DEVI void gate_phase(const Params& p, int j) {
;     ...
; #pragma unroll
;     for (int q = 0; q < 4; ++q) {
;       const int h = q * 2 + half;
;       const float r = rsqrtf(ss[q] * (1.f / 128.f) + 1e-6f);
;       const float o[4] = {bflo(ov[q].x), bfhi(ov[q].x), bflo(ov[q].y), bfhi(ov[q].y)};
;       const float zz[4] = {bflo(zv[q].x), bfhi(zv[q].x), bflo(zv[q].y), bfhi(zv[q].y)};
;       float y[4];
; #pragma unroll
;       for (int e = 0; e < 4; ++e) y[e] = o[e] * r * w[e] * (zz[e] / (1.f + __expf(-zz[e])));
;       *(u32x2*)(r1 + (size_t)t * 3072 + h * 128 + l31 * 4) = u32x2{pack2(y[0], y[1]), pack2(y[2], y[3])};
	v_mul_f32_e32 v168, 0xbfb8aa3b, v166
	v_mul_f32_e32 v169, 0xbfb8aa3b, v167
	v_exp_f32_e32 v168, v168
	v_exp_f32_e32 v169, v169
	v_lshlrev_b32_e32 v170, 16, v56
	v_and_b32_e32 v171, 0xffff0000, v56
	v_add_f32_e32 v168, 1.0, v168
	v_add_f32_e32 v169, 1.0, v169
	v_rcp_f32_e32 v168, v168
	v_rcp_f32_e32 v169, v169
	v_mul_f32_e32 v170, v170, v182
	v_mul_f32_e32 v171, v171, v182
	v_mul_f32_e32 v166, v166, v168
	v_mul_f32_e32 v167, v167, v169
	v_mul_f32_e32 v170, v170, v142
	v_mul_f32_e32 v171, v171, v143
	v_mul_f32_e32 v170, v170, v166
	v_mul_f32_e32 v171, v171, v167
	v_cvt_pk_bf16_f32 v56, v170, v171
	v_lshlrev_b32_e32 v166, 16, v121
	v_and_b32_e32 v167, 0xffff0000, v121
	v_mul_f32_e32 v168, 0xbfb8aa3b, v166
	v_mul_f32_e32 v169, 0xbfb8aa3b, v167
	v_exp_f32_e32 v168, v168
	v_exp_f32_e32 v169, v169
	v_lshlrev_b32_e32 v170, 16, v57
	v_and_b32_e32 v171, 0xffff0000, v57
	v_add_f32_e32 v168, 1.0, v168
	v_add_f32_e32 v169, 1.0, v169
	v_rcp_f32_e32 v168, v168
	v_rcp_f32_e32 v169, v169
	v_mul_f32_e32 v170, v170, v182
	v_mul_f32_e32 v171, v171, v182
	v_mul_f32_e32 v166, v166, v168
	v_mul_f32_e32 v167, v167, v169
	v_mul_f32_e32 v170, v170, v144
	v_mul_f32_e32 v171, v171, v145
	v_mul_f32_e32 v170, v170, v166
	v_mul_f32_e32 v171, v171, v167
	v_cvt_pk_bf16_f32 v57, v170, v171
	v_lshlrev_b32_e32 v166, 16, v122
	v_and_b32_e32 v167, 0xffff0000, v122
	v_mul_f32_e32 v168, 0xbfb8aa3b, v166
	v_mul_f32_e32 v169, 0xbfb8aa3b, v167
	v_exp_f32_e32 v168, v168
	v_exp_f32_e32 v169, v169
	v_lshlrev_b32_e32 v170, 16, v58
	v_and_b32_e32 v171, 0xffff0000, v58
	v_add_f32_e32 v168, 1.0, v168
	v_add_f32_e32 v169, 1.0, v169
	v_rcp_f32_e32 v168, v168
	v_rcp_f32_e32 v169, v169
	v_mul_f32_e32 v170, v170, v182
	v_mul_f32_e32 v171, v171, v182
	v_mul_f32_e32 v166, v166, v168
	v_mul_f32_e32 v167, v167, v169
	v_mul_f32_e32 v170, v170, v146
	v_mul_f32_e32 v171, v171, v147
	v_mul_f32_e32 v170, v170, v166
	v_mul_f32_e32 v171, v171, v167
	v_cvt_pk_bf16_f32 v58, v170, v171
	v_lshlrev_b32_e32 v166, 16, v123
	v_and_b32_e32 v167, 0xffff0000, v123
	v_mul_f32_e32 v168, 0xbfb8aa3b, v166
	v_mul_f32_e32 v169, 0xbfb8aa3b, v167
	v_exp_f32_e32 v168, v168
	v_exp_f32_e32 v169, v169
	v_lshlrev_b32_e32 v170, 16, v59
	v_and_b32_e32 v171, 0xffff0000, v59
	v_add_f32_e32 v168, 1.0, v168
	v_add_f32_e32 v169, 1.0, v169
	v_rcp_f32_e32 v168, v168
	v_rcp_f32_e32 v169, v169
	v_mul_f32_e32 v170, v170, v182
	v_mul_f32_e32 v171, v171, v182
	v_mul_f32_e32 v166, v166, v168
	v_mul_f32_e32 v167, v167, v169
	v_mul_f32_e32 v170, v170, v148
	v_mul_f32_e32 v171, v171, v149
	v_mul_f32_e32 v170, v170, v166
	v_mul_f32_e32 v171, v171, v167
	v_cvt_pk_bf16_f32 v59, v170, v171
	v_lshlrev_b32_e32 v166, 16, v124
	v_and_b32_e32 v167, 0xffff0000, v124
	v_mul_f32_e32 v168, 0xbfb8aa3b, v166
	v_mul_f32_e32 v169, 0xbfb8aa3b, v167
	v_exp_f32_e32 v168, v168
	v_exp_f32_e32 v169, v169
	v_lshlrev_b32_e32 v170, 16, v60
	v_and_b32_e32 v171, 0xffff0000, v60
	v_add_f32_e32 v168, 1.0, v168
	v_add_f32_e32 v169, 1.0, v169
	v_rcp_f32_e32 v168, v168
	v_rcp_f32_e32 v169, v169
	v_mul_f32_e32 v170, v170, v182
	v_mul_f32_e32 v171, v171, v182
	v_mul_f32_e32 v166, v166, v168
	v_mul_f32_e32 v167, v167, v169
	v_mul_f32_e32 v170, v170, v150
	v_mul_f32_e32 v171, v171, v151
	v_mul_f32_e32 v170, v170, v166
	v_mul_f32_e32 v171, v171, v167
	v_cvt_pk_bf16_f32 v60, v170, v171
	v_lshlrev_b32_e32 v166, 16, v125
	v_and_b32_e32 v167, 0xffff0000, v125
	v_mul_f32_e32 v168, 0xbfb8aa3b, v166
	v_mul_f32_e32 v169, 0xbfb8aa3b, v167
	v_exp_f32_e32 v168, v168
	v_exp_f32_e32 v169, v169
	v_lshlrev_b32_e32 v170, 16, v61
	v_and_b32_e32 v171, 0xffff0000, v61
	v_add_f32_e32 v168, 1.0, v168
	v_add_f32_e32 v169, 1.0, v169
	v_rcp_f32_e32 v168, v168
	v_rcp_f32_e32 v169, v169
	v_mul_f32_e32 v170, v170, v182
	v_mul_f32_e32 v171, v171, v182
	v_mul_f32_e32 v166, v166, v168
	v_mul_f32_e32 v167, v167, v169
	v_mul_f32_e32 v170, v170, v152
	v_mul_f32_e32 v171, v171, v153
; DEVI float bflo(unsigned u) { return __uint_as_float(u << 16); }
; DEVI float bfhi(unsigned u) { return __uint_as_float(u & 0xffff0000u); }
; DEVI void gate_phase(const Params& p, int j) {
;     ...
; #pragma unroll
;     for (int q = 0; q < 4; ++q) {
;       const int h = q * 2 + half;
;       const float r = rsqrtf(ss[q] * (1.f / 128.f) + 1e-6f);
;       const float o[4] = {bflo(ov[q].x), bfhi(ov[q].x), bflo(ov[q].y), bfhi(ov[q].y)};
;       const float zz[4] = {bflo(zv[q].x), bfhi(zv[q].x), bflo(zv[q].y), bfhi(zv[q].y)};
;       float y[4];
; #pragma unroll
;       for (int e = 0; e < 4; ++e) y[e] = o[e] * r * w[e] * (zz[e] / (1.f + __expf(-zz[e])));
;       *(u32x2*)(r1 + (size_t)t * 3072 + h * 128 + l31 * 4) = u32x2{pack2(y[0], y[1]), pack2(y[2], y[3])};
;     }
;   }
	v_mul_f32_e32 v170, v170, v166
	v_mul_f32_e32 v171, v171, v167
	v_cvt_pk_bf16_f32 v61, v170, v171
	v_lshlrev_b32_e32 v166, 16, v126
	v_and_b32_e32 v167, 0xffff0000, v126
	v_mul_f32_e32 v168, 0xbfb8aa3b, v166
	v_mul_f32_e32 v169, 0xbfb8aa3b, v167
	v_exp_f32_e32 v168, v168
	v_exp_f32_e32 v169, v169
	v_lshlrev_b32_e32 v170, 16, v62
	v_and_b32_e32 v171, 0xffff0000, v62
	v_add_f32_e32 v168, 1.0, v168
	v_add_f32_e32 v169, 1.0, v169
	v_rcp_f32_e32 v168, v168
	v_rcp_f32_e32 v169, v169
	v_mul_f32_e32 v170, v170, v182
	v_mul_f32_e32 v171, v171, v182
	v_mul_f32_e32 v166, v166, v168
	v_mul_f32_e32 v167, v167, v169
	v_mul_f32_e32 v170, v170, v154
	v_mul_f32_e32 v171, v171, v155
	v_mul_f32_e32 v170, v170, v166
	v_mul_f32_e32 v171, v171, v167
	v_cvt_pk_bf16_f32 v62, v170, v171
	v_lshlrev_b32_e32 v166, 16, v127
	v_and_b32_e32 v167, 0xffff0000, v127
	v_mul_f32_e32 v168, 0xbfb8aa3b, v166
	v_mul_f32_e32 v169, 0xbfb8aa3b, v167
	v_exp_f32_e32 v168, v168
	v_exp_f32_e32 v169, v169
	v_lshlrev_b32_e32 v170, 16, v63
	v_and_b32_e32 v171, 0xffff0000, v63
	v_add_f32_e32 v168, 1.0, v168
	v_add_f32_e32 v169, 1.0, v169
	v_rcp_f32_e32 v168, v168
	v_rcp_f32_e32 v169, v169
	v_mul_f32_e32 v170, v170, v182
	v_mul_f32_e32 v171, v171, v182
	v_mul_f32_e32 v166, v166, v168
	v_mul_f32_e32 v167, v167, v169
	v_mul_f32_e32 v170, v170, v156
	v_mul_f32_e32 v171, v171, v157
	v_mul_f32_e32 v170, v170, v166
	v_mul_f32_e32 v171, v171, v167
	v_cvt_pk_bf16_f32 v63, v170, v171
	v_lshlrev_b32_e32 v166, 16, v128
	v_and_b32_e32 v167, 0xffff0000, v128
	v_mul_f32_e32 v168, 0xbfb8aa3b, v166
	v_mul_f32_e32 v169, 0xbfb8aa3b, v167
	v_exp_f32_e32 v168, v168
	v_exp_f32_e32 v169, v169
	v_lshlrev_b32_e32 v170, 16, v64
	v_and_b32_e32 v171, 0xffff0000, v64
	v_add_f32_e32 v168, 1.0, v168
	v_add_f32_e32 v169, 1.0, v169
	v_rcp_f32_e32 v168, v168
	v_rcp_f32_e32 v169, v169
	v_mul_f32_e32 v170, v170, v182
	v_mul_f32_e32 v171, v171, v182
	v_mul_f32_e32 v166, v166, v168
	v_mul_f32_e32 v167, v167, v169
	v_mul_f32_e32 v170, v170, v158
	v_mul_f32_e32 v171, v171, v159
	v_mul_f32_e32 v170, v170, v166
	v_mul_f32_e32 v171, v171, v167
	v_cvt_pk_bf16_f32 v64, v170, v171
	v_lshlrev_b32_e32 v166, 16, v129
	v_and_b32_e32 v167, 0xffff0000, v129
	v_mul_f32_e32 v168, 0xbfb8aa3b, v166
	v_mul_f32_e32 v169, 0xbfb8aa3b, v167
	v_exp_f32_e32 v168, v168
	v_exp_f32_e32 v169, v169
	v_lshlrev_b32_e32 v170, 16, v65
	v_and_b32_e32 v171, 0xffff0000, v65
	v_add_f32_e32 v168, 1.0, v168
	v_add_f32_e32 v169, 1.0, v169
	v_rcp_f32_e32 v168, v168
	v_rcp_f32_e32 v169, v169
	v_mul_f32_e32 v170, v170, v182
	v_mul_f32_e32 v171, v171, v182
	v_mul_f32_e32 v166, v166, v168
	v_mul_f32_e32 v167, v167, v169
	v_mul_f32_e32 v170, v170, v160
	v_mul_f32_e32 v171, v171, v161
	v_mul_f32_e32 v170, v170, v166
	v_mul_f32_e32 v171, v171, v167
	v_cvt_pk_bf16_f32 v65, v170, v171
	global_store_dwordx4 v162, v[2:5], s[10:11] offset:0
	global_store_dwordx4 v162, v[6:9], s[10:11] offset:16
	global_store_dwordx4 v162, v[10:13], s[10:11] offset:32
	global_store_dwordx4 v162, v[14:17], s[10:11] offset:48
	global_store_dwordx4 v162, v[18:21], s[10:11] offset:64
	global_store_dwordx4 v162, v[22:25], s[10:11] offset:80
	global_store_dwordx4 v162, v[26:29], s[10:11] offset:96
	global_store_dwordx4 v162, v[30:33], s[10:11] offset:112
	global_store_dwordx4 v162, v[34:37], s[10:11] offset:128
	global_store_dwordx4 v162, v[38:41], s[10:11] offset:144
	global_store_dwordx4 v162, v[42:45], s[10:11] offset:160
	global_store_dwordx4 v162, v[46:49], s[10:11] offset:176
	global_store_dwordx4 v162, v[50:53], s[10:11] offset:192
	global_store_dwordx4 v162, v[54:57], s[10:11] offset:208
	global_store_dwordx4 v162, v[58:61], s[10:11] offset:224
	global_store_dwordx4 v162, v[62:65], s[10:11] offset:240
	s_add_u32 s5, s5, 0x800
	v_add_u32_e32 v192, 0x800, v192
	s_branch .Lgt_item
.Lgt_done:
	s_waitcnt vmcnt(0)
.LBB0_351:
	s_mov_b32 s2, 0x800000
	s_or_b64 exec, exec, s[6:7]
	s_mov_b64 s[0:1], 0
